# stacked: q/k-norm rows and K-cache loads de-serialised in phase 3, ada GEMV tile with 16 loads in flight in phase 0, grid barrier tail polling one top counter
# speedup vs baseline: 1.1109x; 1.0104x over previous
.LBB0_583:
	s_waitcnt vmcnt(0)
	v_ashrrev_i32_e32 v24, 6, v166
	v_readlane_b32 s0, v254, 36
	v_and_b32_e32 v83, 63, v166
	s_nop 0
	v_add_u32_e32 v10, s0, v24
	s_movk_i32 s0, 0x2080
	v_cmp_gt_i32_e32 vcc, s0, v10
	s_and_saveexec_b64 s[42:43], vcc
	s_cbranch_execz .LBB0_610
	v_ashrrev_i32_e32 v11, 31, v10
	v_lshlrev_b64 v[2:3], 12, v[10:11]
	v_lshl_add_u64 v[12:13], s[6:7], 0, v[2:3]
	v_mov_b32_e32 v11, v10
	v_lshlrev_b32_e32 v16, 4, v83
	v_mov_b32_e32 v17, v1
	v_lshl_add_u64 v[14:15], v[12:13], 0, v[16:17]
	global_load_dwordx4 v[40:43], v[14:15], off
	global_load_dwordx4 v[44:47], v[14:15], off offset:1024
	global_load_dwordx4 v[48:51], v[14:15], off offset:2048
	global_load_dwordx4 v[52:55], v[14:15], off offset:3072
	v_readlane_b32 s84, v255, 9
	v_readlane_b32 s85, v255, 10
	v_readlane_b32 s86, v255, 11
	v_readlane_b32 s87, v255, 12
	v_readlane_b32 s38, v253, 52
	v_readlane_b32 s39, v253, 53
	v_and_b32_e32 v0, 7, v83
	v_lshlrev_b32_e32 v0, 5, v0
	v_lshlrev_b32_e32 v148, 5, v83
	s_mov_b32 s36, 0x3e000000
	global_load_dwordx4 v[72:75], v0, s[84:85]
	global_load_dwordx4 v[76:79], v0, s[84:85] offset:16
	global_load_dwordx4 v[84:87], v0, s[86:87]
	global_load_dwordx4 v[88:91], v0, s[86:87] offset:16
.Lqk_row:
	s_waitcnt vmcnt(0)
	v_mov_b32_e32 v56, v40
	v_mov_b32_e32 v57, v41
	v_mov_b32_e32 v58, v42
	v_mov_b32_e32 v59, v43
	v_mov_b32_e32 v60, v44
	v_mov_b32_e32 v61, v45
	v_mov_b32_e32 v62, v46
	v_mov_b32_e32 v63, v47
	v_mov_b32_e32 v64, v48
	v_mov_b32_e32 v65, v49
	v_mov_b32_e32 v66, v50
	v_mov_b32_e32 v67, v51
	v_mov_b32_e32 v68, v52
	v_mov_b32_e32 v69, v53
	v_mov_b32_e32 v70, v54
	v_mov_b32_e32 v71, v55
	v_mov_b32_e32 v150, v11
	v_mov_b64_e32 v[94:95], v[14:15]
	v_add_u32_e32 v11, s56, v11
	v_cmp_ge_i32_e32 vcc, s67, v11
	s_mov_b64 s[44:45], vcc
	s_cbranch_vccz .Lqk_nopf
	v_lshl_add_u64 v[14:15], v[14:15], 0, s[38:39]
	global_load_dwordx4 v[40:43], v[14:15], off
	global_load_dwordx4 v[44:47], v[14:15], off offset:1024
	global_load_dwordx4 v[48:51], v[14:15], off offset:2048
	global_load_dwordx4 v[52:55], v[14:15], off offset:3072
.Lqk_nopf:
	v_lshlrev_b32_e32 v96, 16, v56
	v_and_b32_e32 v97, 0xffff0000, v56
	v_lshlrev_b32_e32 v98, 16, v57
	v_and_b32_e32 v99, 0xffff0000, v57
	v_lshlrev_b32_e32 v100, 16, v58
	v_and_b32_e32 v101, 0xffff0000, v58
	v_lshlrev_b32_e32 v102, 16, v59
	v_and_b32_e32 v103, 0xffff0000, v59
	v_lshlrev_b32_e32 v104, 16, v60
	v_and_b32_e32 v105, 0xffff0000, v60
	v_lshlrev_b32_e32 v106, 16, v61
	v_and_b32_e32 v107, 0xffff0000, v61
	v_lshlrev_b32_e32 v108, 16, v62
	v_and_b32_e32 v109, 0xffff0000, v62
	v_lshlrev_b32_e32 v110, 16, v63
	v_and_b32_e32 v111, 0xffff0000, v63
	v_lshlrev_b32_e32 v112, 16, v64
	v_and_b32_e32 v113, 0xffff0000, v64
	v_lshlrev_b32_e32 v114, 16, v65
	v_and_b32_e32 v115, 0xffff0000, v65
	v_lshlrev_b32_e32 v116, 16, v66
	v_and_b32_e32 v117, 0xffff0000, v66
	v_lshlrev_b32_e32 v118, 16, v67
	v_and_b32_e32 v119, 0xffff0000, v67
	v_lshlrev_b32_e32 v120, 16, v68
	v_and_b32_e32 v121, 0xffff0000, v68
	v_lshlrev_b32_e32 v122, 16, v69
	v_and_b32_e32 v123, 0xffff0000, v69
	v_lshlrev_b32_e32 v124, 16, v70
	v_and_b32_e32 v125, 0xffff0000, v70
	v_lshlrev_b32_e32 v126, 16, v71
	v_and_b32_e32 v127, 0xffff0000, v71
	v_pk_mul_f32 v[132:133], v[96:97], v[96:97]
	v_pk_mul_f32 v[134:135], v[98:99], v[98:99]
	v_pk_mul_f32 v[136:137], v[100:101], v[100:101]
	v_pk_mul_f32 v[138:139], v[102:103], v[102:103]
	v_add_f32_e32 v128, v132, v133
	v_add_f32_e32 v128, v134, v128
	v_add_f32_e32 v128, v135, v128
	v_add_f32_e32 v128, v136, v128
	v_add_f32_e32 v128, v137, v128
	v_add_f32_e32 v128, v138, v128
	v_add_f32_e32 v128, v139, v128
	v_pk_mul_f32 v[132:133], v[104:105], v[104:105]
	v_pk_mul_f32 v[134:135], v[106:107], v[106:107]
	v_pk_mul_f32 v[136:137], v[108:109], v[108:109]
	v_pk_mul_f32 v[138:139], v[110:111], v[110:111]
	v_add_f32_e32 v129, v132, v133
	v_add_f32_e32 v129, v134, v129
	v_add_f32_e32 v129, v135, v129
	v_add_f32_e32 v129, v136, v129
	v_add_f32_e32 v129, v137, v129
	v_add_f32_e32 v129, v138, v129
	v_add_f32_e32 v129, v139, v129
	v_pk_mul_f32 v[132:133], v[112:113], v[112:113]
	v_pk_mul_f32 v[134:135], v[114:115], v[114:115]
	v_pk_mul_f32 v[136:137], v[116:117], v[116:117]
	v_pk_mul_f32 v[138:139], v[118:119], v[118:119]
	v_add_f32_e32 v130, v132, v133
	v_add_f32_e32 v130, v134, v130
	v_add_f32_e32 v130, v135, v130
	v_add_f32_e32 v130, v136, v130
	v_add_f32_e32 v130, v137, v130
	v_add_f32_e32 v130, v138, v130
	v_add_f32_e32 v130, v139, v130
	v_pk_mul_f32 v[132:133], v[120:121], v[120:121]
	v_pk_mul_f32 v[134:135], v[122:123], v[122:123]
	v_pk_mul_f32 v[136:137], v[124:125], v[124:125]
	v_pk_mul_f32 v[138:139], v[126:127], v[126:127]
	v_add_f32_e32 v131, v132, v133
	v_add_f32_e32 v131, v134, v131
	v_add_f32_e32 v131, v135, v131
	v_add_f32_e32 v131, v136, v131
	v_add_f32_e32 v131, v137, v131
	v_add_f32_e32 v131, v138, v131
	v_add_f32_e32 v131, v139, v131
	v_add_f32_dpp v128, v128, v128 quad_perm:[1,0,3,2] row_mask:0xf bank_mask:0xf
	v_add_f32_dpp v129, v129, v129 quad_perm:[1,0,3,2] row_mask:0xf bank_mask:0xf
	v_add_f32_dpp v130, v130, v130 quad_perm:[1,0,3,2] row_mask:0xf bank_mask:0xf
	v_add_f32_dpp v131, v131, v131 quad_perm:[1,0,3,2] row_mask:0xf bank_mask:0xf
	v_add_f32_dpp v128, v128, v128 quad_perm:[2,3,0,1] row_mask:0xf bank_mask:0xf
	v_add_f32_dpp v129, v129, v129 quad_perm:[2,3,0,1] row_mask:0xf bank_mask:0xf
	v_add_f32_dpp v130, v130, v130 quad_perm:[2,3,0,1] row_mask:0xf bank_mask:0xf
	v_add_f32_dpp v131, v131, v131 quad_perm:[2,3,0,1] row_mask:0xf bank_mask:0xf
	v_add_f32_dpp v128, v128, v128 row_half_mirror row_mask:0xf bank_mask:0xf
	v_add_f32_dpp v129, v129, v129 row_half_mirror row_mask:0xf bank_mask:0xf
	v_add_f32_dpp v130, v130, v130 row_half_mirror row_mask:0xf bank_mask:0xf
	v_add_f32_dpp v131, v131, v131 row_half_mirror row_mask:0xf bank_mask:0xf
	s_nop 1
	v_fmamk_f32 v128, v128, 0x3c800000, v158
	v_mul_f32_e32 v152, 0x4b800000, v128
	v_cmp_gt_f32_e64 s[40:41], s5, v128
	s_nop 1
	v_cndmask_b32_e64 v128, v128, v152, s[40:41]
	v_rsq_f32_e32 v128, v128
	s_nop 0
	v_mul_f32_e32 v152, 0x45800000, v128
	v_cndmask_b32_e64 v140, v128, v152, s[40:41]
	v_fmamk_f32 v129, v129, 0x3c800000, v158
	v_mul_f32_e32 v152, 0x4b800000, v129
	v_cmp_gt_f32_e64 s[40:41], s5, v129
	s_nop 1
	v_cndmask_b32_e64 v129, v129, v152, s[40:41]
	v_rsq_f32_e32 v129, v129
	s_nop 0
	v_mul_f32_e32 v152, 0x45800000, v129
	v_cndmask_b32_e64 v142, v129, v152, s[40:41]
	v_fmamk_f32 v130, v130, 0x3c800000, v158
	v_mul_f32_e32 v152, 0x4b800000, v130
	v_cmp_gt_f32_e64 s[40:41], s5, v130
	s_nop 1
	v_cndmask_b32_e64 v130, v130, v152, s[40:41]
	v_rsq_f32_e32 v130, v130
	s_nop 0
	v_mul_f32_e32 v152, 0x45800000, v130
	v_cndmask_b32_e64 v144, v130, v152, s[40:41]
	v_fmamk_f32 v131, v131, 0x3c800000, v158
	v_mul_f32_e32 v152, 0x4b800000, v131
	v_cmp_gt_f32_e64 s[40:41], s5, v131
	s_nop 1
	v_cndmask_b32_e64 v131, v131, v152, s[40:41]
	v_rsq_f32_e32 v131, v131
	s_nop 0
	v_mul_f32_e32 v152, 0x45800000, v131
	v_cndmask_b32_e64 v146, v131, v152, s[40:41]
	v_pk_mul_f32 v[96:97], v[140:141], v[96:97] op_sel_hi:[0,1]
	v_pk_mul_f32 v[96:97], v[72:73], v[96:97]
	v_pk_mul_f32 v[96:97], v[96:97], s[36:37] op_sel_hi:[1,0]
	v_pk_mul_f32 v[98:99], v[140:141], v[98:99] op_sel_hi:[0,1]
	v_pk_mul_f32 v[98:99], v[74:75], v[98:99]
	v_pk_mul_f32 v[98:99], v[98:99], s[36:37] op_sel_hi:[1,0]
	v_pk_mul_f32 v[100:101], v[140:141], v[100:101] op_sel_hi:[0,1]
	v_pk_mul_f32 v[100:101], v[76:77], v[100:101]
	v_pk_mul_f32 v[100:101], v[100:101], s[36:37] op_sel_hi:[1,0]
	v_pk_mul_f32 v[102:103], v[140:141], v[102:103] op_sel_hi:[0,1]
	v_pk_mul_f32 v[102:103], v[78:79], v[102:103]
	v_pk_mul_f32 v[102:103], v[102:103], s[36:37] op_sel_hi:[1,0]
	v_pk_mul_f32 v[104:105], v[142:143], v[104:105] op_sel_hi:[0,1]
	v_pk_mul_f32 v[104:105], v[72:73], v[104:105]
	v_pk_mul_f32 v[104:105], v[104:105], s[36:37] op_sel_hi:[1,0]
	v_pk_mul_f32 v[106:107], v[142:143], v[106:107] op_sel_hi:[0,1]
	v_pk_mul_f32 v[106:107], v[74:75], v[106:107]
	v_pk_mul_f32 v[106:107], v[106:107], s[36:37] op_sel_hi:[1,0]
	v_pk_mul_f32 v[108:109], v[142:143], v[108:109] op_sel_hi:[0,1]
	v_pk_mul_f32 v[108:109], v[76:77], v[108:109]
	v_pk_mul_f32 v[108:109], v[108:109], s[36:37] op_sel_hi:[1,0]
	v_pk_mul_f32 v[110:111], v[142:143], v[110:111] op_sel_hi:[0,1]
	v_pk_mul_f32 v[110:111], v[78:79], v[110:111]
	v_pk_mul_f32 v[110:111], v[110:111], s[36:37] op_sel_hi:[1,0]
	v_pk_mul_f32 v[112:113], v[144:145], v[112:113] op_sel_hi:[0,1]
	v_pk_mul_f32 v[112:113], v[84:85], v[112:113]
	v_pk_mul_f32 v[114:115], v[144:145], v[114:115] op_sel_hi:[0,1]
	v_pk_mul_f32 v[114:115], v[86:87], v[114:115]
	v_pk_mul_f32 v[116:117], v[144:145], v[116:117] op_sel_hi:[0,1]
	v_pk_mul_f32 v[116:117], v[88:89], v[116:117]
	v_pk_mul_f32 v[118:119], v[144:145], v[118:119] op_sel_hi:[0,1]
	v_pk_mul_f32 v[118:119], v[90:91], v[118:119]
	v_pk_mul_f32 v[120:121], v[146:147], v[120:121] op_sel_hi:[0,1]
	v_pk_mul_f32 v[120:121], v[84:85], v[120:121]
	v_pk_mul_f32 v[122:123], v[146:147], v[122:123] op_sel_hi:[0,1]
	v_pk_mul_f32 v[122:123], v[86:87], v[122:123]
	v_pk_mul_f32 v[124:125], v[146:147], v[124:125] op_sel_hi:[0,1]
	v_pk_mul_f32 v[124:125], v[88:89], v[124:125]
	v_pk_mul_f32 v[126:127], v[146:147], v[126:127] op_sel_hi:[0,1]
	v_pk_mul_f32 v[126:127], v[90:91], v[126:127]
	v_readfirstlane_b32 s12, v150
	s_cmpk_gt_u32 s12, 0x1fff
	s_cbranch_scc1 .Lqk_samp
	s_and_b32 s13, s12, 0x7ff
	s_cmpk_lt_u32 s13, 0x600
	s_cbranch_scc1 .Lqk_noside
	s_lshr_b32 s0, s12, 11
	s_lshl_b32 s0, s0, 21
	s_sub_u32 s13, s13, 0x600
	s_lshl_b32 s13, s13, 12
	s_add_u32 s0, s0, s13
	v_readlane_b32 s40, v250, 57
	v_readlane_b32 s41, v250, 58
	s_add_u32 s40, s40, s0
	s_addc_u32 s41, s41, 0
	s_branch .Lqk_side
.Lqk_samp:
	s_sub_u32 s0, s12, 0x2000
	s_lshl_b32 s0, s0, 12
	v_readlane_b32 s40, v250, 59
	v_readlane_b32 s41, v250, 60
	s_add_u32 s40, s40, s0
	s_addc_u32 s41, s41, 0
.Lqk_side:
	global_store_dwordx4 v148, v[112:115], s[40:41]
	global_store_dwordx4 v148, v[116:119], s[40:41] offset:16
	global_store_dwordx4 v148, v[120:123], s[40:41] offset:2048
	global_store_dwordx4 v148, v[124:127], s[40:41] offset:2064
.Lqk_noside:
	v_cvt_pk_bf16_f32 v2, v96, v97
	v_cvt_pk_bf16_f32 v3, v98, v99
	v_cvt_pk_bf16_f32 v4, v100, v101
	v_cvt_pk_bf16_f32 v5, v102, v103
	global_store_dwordx4 v[94:95], v[2:5], off
	v_cvt_pk_bf16_f32 v6, v104, v105
	v_cvt_pk_bf16_f32 v7, v106, v107
	v_cvt_pk_bf16_f32 v8, v108, v109
	v_cvt_pk_bf16_f32 v9, v110, v111
	global_store_dwordx4 v[94:95], v[6:9], off offset:1024
	v_cvt_pk_bf16_f32 v16, v112, v113
	v_cvt_pk_bf16_f32 v17, v114, v115
	v_cvt_pk_bf16_f32 v18, v116, v117
	v_cvt_pk_bf16_f32 v19, v118, v119
	global_store_dwordx4 v[94:95], v[16:19], off offset:2048
	v_cvt_pk_bf16_f32 v20, v120, v121
	v_cvt_pk_bf16_f32 v21, v122, v123
	v_cvt_pk_bf16_f32 v22, v124, v125
	v_cvt_pk_bf16_f32 v23, v126, v127
	global_store_dwordx4 v[94:95], v[20:23], off offset:3072
	s_mov_b64 vcc, s[44:45]
	s_cbranch_vccnz .Lqk_row

.LBB0_612:
	global_load_dwordx4 v[44:47], v[4:5], off offset:-16 nt
	global_load_dwordx4 v[48:51], v[4:5], off nt
	v_lshl_add_u64 v[4:5], v[4:5], 0, s[40:41]
	global_load_dwordx4 v[52:55], v[4:5], off offset:-16 nt
	global_load_dwordx4 v[56:59], v[4:5], off nt
	v_lshl_add_u64 v[4:5], v[4:5], 0, s[40:41]
	global_load_dwordx4 v[60:63], v[4:5], off offset:-16 nt
	global_load_dwordx4 v[64:67], v[4:5], off nt
	v_lshl_add_u64 v[4:5], v[4:5], 0, s[40:41]
	global_load_dwordx4 v[68:71], v[4:5], off offset:-16 nt
	global_load_dwordx4 v[72:75], v[4:5], off nt
	s_waitcnt vmcnt(6)
	v_cvt_pk_bf16_f32 v44, v44, v45
	v_cvt_pk_bf16_f32 v45, v46, v47
	v_cvt_pk_bf16_f32 v46, v48, v49
	v_cvt_pk_bf16_f32 v47, v50, v51
	s_waitcnt vmcnt(4)
	v_cvt_pk_bf16_f32 v52, v52, v53
	v_cvt_pk_bf16_f32 v53, v54, v55
	v_cvt_pk_bf16_f32 v54, v56, v57
	v_cvt_pk_bf16_f32 v55, v58, v59
	s_waitcnt vmcnt(2)
	v_cvt_pk_bf16_f32 v60, v60, v61
	v_cvt_pk_bf16_f32 v61, v62, v63
	v_cvt_pk_bf16_f32 v62, v64, v65
	v_cvt_pk_bf16_f32 v63, v66, v67
	s_waitcnt vmcnt(0)
	v_cvt_pk_bf16_f32 v68, v68, v69
	v_cvt_pk_bf16_f32 v69, v70, v71
	v_cvt_pk_bf16_f32 v70, v72, v73
	v_cvt_pk_bf16_f32 v71, v74, v75
	global_store_dwordx4 v[6:7], v[44:47], off
	v_lshl_add_u64 v[6:7], v[6:7], 0, s[38:39]
	global_store_dwordx4 v[6:7], v[52:55], off
	v_lshl_add_u64 v[6:7], v[6:7], 0, s[38:39]
	global_store_dwordx4 v[6:7], v[60:63], off
	v_lshl_add_u64 v[6:7], v[6:7], 0, s[38:39]
	global_store_dwordx4 v[6:7], v[68:71], off

.LBB0_832:
	s_mul_hi_i32 s12, s36, 0x2aaaaaab
	s_lshr_b32 s13, s12, 31
	s_ashr_i32 s12, s12, 3
	s_add_i32 s12, s12, s13
	s_lshl_b32 s13, s12, 8
	s_barrier
	v_readlane_b32 s72, v253, 58
	v_readlane_b32 s73, v253, 59
	v_readlane_b32 s74, v253, 60
	v_readlane_b32 s75, v253, 61
	v_readlane_b32 s76, v253, 62
	v_readlane_b32 s77, v253, 63
	v_readlane_b32 s78, v254, 0
	v_readlane_b32 s79, v254, 1
	v_readlane_b32 s80, v254, 2
	v_readlane_b32 s81, v254, 3
	v_readlane_b32 s82, v254, 4
	v_readlane_b32 s83, v254, 5
	v_readlane_b32 s84, v254, 6
	v_readlane_b32 s85, v254, 7
	v_readlane_b32 s86, v254, 8
	v_readlane_b32 s87, v254, 9
	s_movk_i32 s48, 0x9ff
	s_mul_i32 s42, s12, 48
	s_sub_i32 s42, s36, s42
	s_lshl_b32 s42, s42, 8
	s_ashr_i32 s43, s42, 31
	s_lshl_b64 s[44:45], s[42:43], 2
	v_add_u32_e32 v0, s13, v115
	v_mov_b64_e32 v[2:3], s[44:45]
	s_mov_b32 s46, 0xc000
	v_mad_i64_i32 v[2:3], s[44:45], v0, s46, v[2:3]
	v_lshl_add_u64 v[110:111], v[108:109], 0, v[2:3]
	s_mov_b32 s44, 0xc000
	s_mov_b32 s45, 0
	v_and_b32_e32 v4, 0xff, v166
	v_lshrrev_b32_e32 v5, 8, v166
	v_lshl_add_u32 v4, v5, 11, v4
	v_add_u32_e32 v4, s13, v4
	v_lshlrev_b32_e32 v4, 2, v4
	v_add_u32_e32 v5, 0x4000, v4
	v_add_u32_e32 v10, 0x8000, v4
	v_add_u32_e32 v11, 0xc000, v4
	global_load_dword v6, v4, s[76:77]
	global_load_dword v7, v5, s[76:77]
	global_load_dword v8, v4, s[78:79]
	global_load_dword v9, v5, s[78:79]
	global_load_dword v12, v10, s[78:79]
	global_load_dword v13, v11, s[78:79]
	v_mov_b64_e32 v[196:197], v[110:111]
	global_load_dwordx4 v[98:101], v[196:197], off nt
	v_lshl_add_u64 v[196:197], v[196:197], 0, s[44:45]
	global_load_dwordx4 v[102:105], v[196:197], off nt
	v_lshl_add_u64 v[196:197], v[196:197], 0, s[44:45]
	global_load_dwordx4 v[126:129], v[196:197], off nt
	v_lshl_add_u64 v[196:197], v[196:197], 0, s[44:45]
	global_load_dwordx4 v[130:133], v[196:197], off nt
	v_lshl_add_u64 v[196:197], v[196:197], 0, s[44:45]
	global_load_dwordx4 v[134:137], v[196:197], off nt
	v_lshl_add_u64 v[196:197], v[196:197], 0, s[44:45]
	global_load_dwordx4 v[138:141], v[196:197], off nt
	v_lshl_add_u64 v[196:197], v[196:197], 0, s[44:45]
	global_load_dwordx4 v[142:145], v[196:197], off nt
	v_lshl_add_u64 v[196:197], v[196:197], 0, s[44:45]
	global_load_dwordx4 v[146:149], v[196:197], off nt
	v_lshl_add_u64 v[196:197], v[196:197], 0, s[44:45]
	global_load_dwordx4 v[150:153], v[196:197], off nt
	v_lshl_add_u64 v[196:197], v[196:197], 0, s[44:45]
	global_load_dwordx4 v[168:171], v[196:197], off nt
	v_lshl_add_u64 v[196:197], v[196:197], 0, s[44:45]
	global_load_dwordx4 v[172:175], v[196:197], off nt
	v_lshl_add_u64 v[196:197], v[196:197], 0, s[44:45]
	global_load_dwordx4 v[176:179], v[196:197], off nt
	v_lshl_add_u64 v[196:197], v[196:197], 0, s[44:45]
	global_load_dwordx4 v[180:183], v[196:197], off nt
	v_lshl_add_u64 v[196:197], v[196:197], 0, s[44:45]
	global_load_dwordx4 v[184:187], v[196:197], off nt
	v_lshl_add_u64 v[196:197], v[196:197], 0, s[44:45]
	global_load_dwordx4 v[188:191], v[196:197], off nt
	v_lshl_add_u64 v[196:197], v[196:197], 0, s[44:45]
	global_load_dwordx4 v[192:195], v[196:197], off nt
	v_lshl_add_u64 v[196:197], v[196:197], 0, s[44:45]
	v_mov_b32_e32 v42, 0
	v_mov_b32_e32 v94, v42
	v_mov_b32_e32 v95, v42
	v_mov_b32_e32 v96, v42
	v_mov_b32_e32 v97, v42
	v_mov_b32_e32 v90, v42
	v_mov_b32_e32 v91, v42
	v_mov_b32_e32 v92, v42
	v_mov_b32_e32 v93, v42
	v_mov_b32_e32 v86, v42
	v_mov_b32_e32 v87, v42
	v_mov_b32_e32 v88, v42
	v_mov_b32_e32 v89, v42
	v_mov_b32_e32 v74, v42
	v_mov_b32_e32 v75, v42
	v_mov_b32_e32 v76, v42
	v_mov_b32_e32 v77, v42
	v_mov_b32_e32 v70, v42
	v_mov_b32_e32 v71, v42
	v_mov_b32_e32 v72, v42
	v_mov_b32_e32 v73, v42
	v_mov_b32_e32 v66, v42
	v_mov_b32_e32 v67, v42
	v_mov_b32_e32 v68, v42
	v_mov_b32_e32 v69, v42
	v_mov_b32_e32 v62, v42
	v_mov_b32_e32 v63, v42
	v_mov_b32_e32 v64, v42
	v_mov_b32_e32 v65, v42
	v_mov_b32_e32 v58, v42
	v_mov_b32_e32 v59, v42
	v_mov_b32_e32 v60, v42
	v_mov_b32_e32 v61, v42
	v_mov_b32_e32 v54, v42
	v_mov_b32_e32 v55, v42
	v_mov_b32_e32 v56, v42
	v_mov_b32_e32 v57, v42
	v_mov_b32_e32 v50, v42
	v_mov_b32_e32 v51, v42
	v_mov_b32_e32 v52, v42
	v_mov_b32_e32 v53, v42
	v_mov_b32_e32 v46, v42
	v_mov_b32_e32 v47, v42
	v_mov_b32_e32 v48, v42
	v_mov_b32_e32 v49, v42
	v_mov_b32_e32 v43, v42
	v_mov_b32_e32 v44, v42
	v_mov_b32_e32 v45, v42
	v_mov_b32_e32 v124, v117
	s_waitcnt vmcnt(16)
	v_mul_f32_e32 v14, 0xbfb8aa3b, v6
	v_exp_f32_e32 v14, v14
	s_nop 0
	v_add_f32_e32 v14, 1.0, v14
	v_div_scale_f32 v15, s[46:47], v14, v14, v6
	v_rcp_f32_e32 v16, v15
	v_div_scale_f32 v17, vcc, v6, v14, v6
	v_fma_f32 v18, -v15, v16, 1.0
	v_fmac_f32_e32 v16, v18, v16
	v_mul_f32_e32 v18, v17, v16
	v_fma_f32 v19, -v15, v18, v17
	v_fmac_f32_e32 v18, v19, v16
	v_fma_f32 v15, -v15, v18, v17
	v_div_fmas_f32 v15, v15, v16, v18
	v_div_fixup_f32 v6, v15, v14, v6
	ds_write_b32 v122, v6
	v_mul_f32_e32 v14, 0xbfb8aa3b, v7
	v_exp_f32_e32 v14, v14
	s_nop 0
	v_add_f32_e32 v14, 1.0, v14
	v_div_scale_f32 v15, s[46:47], v14, v14, v7
	v_rcp_f32_e32 v16, v15
	v_div_scale_f32 v17, vcc, v7, v14, v7
	v_fma_f32 v18, -v15, v16, 1.0
	v_fmac_f32_e32 v16, v18, v16
	v_mul_f32_e32 v18, v17, v16
	v_fma_f32 v19, -v15, v18, v17
	v_fmac_f32_e32 v18, v19, v16
	v_fma_f32 v15, -v15, v18, v17
	v_div_fmas_f32 v15, v15, v16, v18
	v_div_fixup_f32 v7, v15, v14, v7
	ds_write_b32 v122, v7 offset:2048
	v_mul_f32_e32 v14, 0xbfb8aa3b, v8
	v_exp_f32_e32 v14, v14
	s_nop 0
	v_add_f32_e32 v14, 1.0, v14
	v_div_scale_f32 v15, s[46:47], v14, v14, v8
	v_rcp_f32_e32 v16, v15
	v_div_scale_f32 v17, vcc, v8, v14, v8
	v_fma_f32 v18, -v15, v16, 1.0
	v_fmac_f32_e32 v16, v18, v16
	v_mul_f32_e32 v18, v17, v16
	v_fma_f32 v19, -v15, v18, v17
	v_fmac_f32_e32 v18, v19, v16
	v_fma_f32 v15, -v15, v18, v17
	v_div_fmas_f32 v15, v15, v16, v18
	v_div_fixup_f32 v8, v15, v14, v8
	ds_write_b32 v122, v8 offset:4096
	v_mul_f32_e32 v14, 0xbfb8aa3b, v9
	v_exp_f32_e32 v14, v14
	s_nop 0
	v_add_f32_e32 v14, 1.0, v14
	v_div_scale_f32 v15, s[46:47], v14, v14, v9
	v_rcp_f32_e32 v16, v15
	v_div_scale_f32 v17, vcc, v9, v14, v9
	v_fma_f32 v18, -v15, v16, 1.0
	v_fmac_f32_e32 v16, v18, v16
	v_mul_f32_e32 v18, v17, v16
	v_fma_f32 v19, -v15, v18, v17
	v_fmac_f32_e32 v18, v19, v16
	v_fma_f32 v15, -v15, v18, v17
	v_div_fmas_f32 v15, v15, v16, v18
	v_div_fixup_f32 v9, v15, v14, v9
	ds_write_b32 v122, v9 offset:6144
	v_mul_f32_e32 v14, 0xbfb8aa3b, v12
	v_exp_f32_e32 v14, v14
	s_nop 0
	v_add_f32_e32 v14, 1.0, v14
	v_div_scale_f32 v15, s[46:47], v14, v14, v12
	v_rcp_f32_e32 v16, v15
	v_div_scale_f32 v17, vcc, v12, v14, v12
	v_fma_f32 v18, -v15, v16, 1.0
	v_fmac_f32_e32 v16, v18, v16
	v_mul_f32_e32 v18, v17, v16
	v_fma_f32 v19, -v15, v18, v17
	v_fmac_f32_e32 v18, v19, v16
	v_fma_f32 v15, -v15, v18, v17
	v_div_fmas_f32 v15, v15, v16, v18
	v_div_fixup_f32 v12, v15, v14, v12
	ds_write_b32 v122, v12 offset:8192
	v_mul_f32_e32 v14, 0xbfb8aa3b, v13
	v_exp_f32_e32 v14, v14
	s_nop 0
	v_add_f32_e32 v14, 1.0, v14
	v_div_scale_f32 v15, s[46:47], v14, v14, v13
	v_rcp_f32_e32 v16, v15
	v_div_scale_f32 v17, vcc, v13, v14, v13
	v_fma_f32 v18, -v15, v16, 1.0
	v_fmac_f32_e32 v16, v18, v16
	v_mul_f32_e32 v18, v17, v16
	v_fma_f32 v19, -v15, v18, v17
	v_fmac_f32_e32 v18, v19, v16
	v_fma_f32 v15, -v15, v18, v17
	v_div_fmas_f32 v15, v15, v16, v18
	v_div_fixup_f32 v13, v15, v14, v13
	ds_write_b32 v122, v13 offset:10240
	s_waitcnt lgkmcnt(0)
	s_barrier
	ds_read_b128 v[2:5], v124 offset:0
	ds_read_b128 v[6:9], v124 offset:1024
	ds_read_b128 v[10:13], v124 offset:2048
	ds_read_b128 v[14:17], v124 offset:3072
	ds_read_b128 v[18:21], v124 offset:4096
	ds_read_b128 v[22:25], v124 offset:5120
	ds_read_b128 v[26:29], v124 offset:6144
	ds_read_b128 v[30:33], v124 offset:7168
	ds_read_b128 v[34:37], v124 offset:8192
	ds_read_b128 v[38:41], v124 offset:9216
	ds_read_b128 v[78:81], v124 offset:10240
	ds_read_b128 v[82:85], v124 offset:11264
	s_waitcnt vmcnt(15) lgkmcnt(0)
	v_pk_fma_f32 v[96:97], v[100:101], v[2:3], v[96:97] op_sel_hi:[1,0,1]
	v_pk_fma_f32 v[94:95], v[98:99], v[2:3], v[94:95] op_sel_hi:[1,0,1]
	v_pk_fma_f32 v[92:93], v[100:101], v[6:7], v[92:93] op_sel_hi:[1,0,1]
	v_pk_fma_f32 v[90:91], v[98:99], v[6:7], v[90:91] op_sel_hi:[1,0,1]
	v_pk_fma_f32 v[88:89], v[100:101], v[10:11], v[88:89] op_sel_hi:[1,0,1]
	v_pk_fma_f32 v[86:87], v[98:99], v[10:11], v[86:87] op_sel_hi:[1,0,1]
	v_pk_fma_f32 v[76:77], v[100:101], v[14:15], v[76:77] op_sel_hi:[1,0,1]
	v_pk_fma_f32 v[74:75], v[98:99], v[14:15], v[74:75] op_sel_hi:[1,0,1]
	v_pk_fma_f32 v[72:73], v[100:101], v[18:19], v[72:73] op_sel_hi:[1,0,1]
	v_pk_fma_f32 v[70:71], v[98:99], v[18:19], v[70:71] op_sel_hi:[1,0,1]
	v_pk_fma_f32 v[68:69], v[100:101], v[22:23], v[68:69] op_sel_hi:[1,0,1]
	v_pk_fma_f32 v[66:67], v[98:99], v[22:23], v[66:67] op_sel_hi:[1,0,1]
	v_pk_fma_f32 v[64:65], v[100:101], v[26:27], v[64:65] op_sel_hi:[1,0,1]
	v_pk_fma_f32 v[62:63], v[98:99], v[26:27], v[62:63] op_sel_hi:[1,0,1]
	v_pk_fma_f32 v[60:61], v[100:101], v[30:31], v[60:61] op_sel_hi:[1,0,1]
	v_pk_fma_f32 v[58:59], v[98:99], v[30:31], v[58:59] op_sel_hi:[1,0,1]
	v_pk_fma_f32 v[56:57], v[100:101], v[34:35], v[56:57] op_sel_hi:[1,0,1]
	v_pk_fma_f32 v[54:55], v[98:99], v[34:35], v[54:55] op_sel_hi:[1,0,1]
	v_pk_fma_f32 v[52:53], v[100:101], v[38:39], v[52:53] op_sel_hi:[1,0,1]
	v_pk_fma_f32 v[50:51], v[98:99], v[38:39], v[50:51] op_sel_hi:[1,0,1]
	v_pk_fma_f32 v[48:49], v[100:101], v[78:79], v[48:49] op_sel_hi:[1,0,1]
	v_pk_fma_f32 v[46:47], v[98:99], v[78:79], v[46:47] op_sel_hi:[1,0,1]
	v_pk_fma_f32 v[44:45], v[100:101], v[82:83], v[44:45] op_sel_hi:[1,0,1]
	v_pk_fma_f32 v[42:43], v[98:99], v[82:83], v[42:43] op_sel_hi:[1,0,1]
	global_load_dwordx4 v[98:101], v[196:197], off nt
	v_lshl_add_u64 v[196:197], v[196:197], 0, s[44:45]
	s_waitcnt vmcnt(15)
	v_pk_fma_f32 v[96:97], v[104:105], v[2:3], v[96:97] op_sel:[0,1,0]
	v_pk_fma_f32 v[94:95], v[102:103], v[2:3], v[94:95] op_sel:[0,1,0]
	v_pk_fma_f32 v[92:93], v[104:105], v[6:7], v[92:93] op_sel:[0,1,0]
	v_pk_fma_f32 v[90:91], v[102:103], v[6:7], v[90:91] op_sel:[0,1,0]
	v_pk_fma_f32 v[88:89], v[104:105], v[10:11], v[88:89] op_sel:[0,1,0]
	v_pk_fma_f32 v[86:87], v[102:103], v[10:11], v[86:87] op_sel:[0,1,0]
	v_pk_fma_f32 v[76:77], v[104:105], v[14:15], v[76:77] op_sel:[0,1,0]
	v_pk_fma_f32 v[74:75], v[102:103], v[14:15], v[74:75] op_sel:[0,1,0]
	v_pk_fma_f32 v[72:73], v[104:105], v[18:19], v[72:73] op_sel:[0,1,0]
	v_pk_fma_f32 v[70:71], v[102:103], v[18:19], v[70:71] op_sel:[0,1,0]
	v_pk_fma_f32 v[68:69], v[104:105], v[22:23], v[68:69] op_sel:[0,1,0]
	v_pk_fma_f32 v[66:67], v[102:103], v[22:23], v[66:67] op_sel:[0,1,0]
	v_pk_fma_f32 v[64:65], v[104:105], v[26:27], v[64:65] op_sel:[0,1,0]
	v_pk_fma_f32 v[62:63], v[102:103], v[26:27], v[62:63] op_sel:[0,1,0]
	v_pk_fma_f32 v[60:61], v[104:105], v[30:31], v[60:61] op_sel:[0,1,0]
	v_pk_fma_f32 v[58:59], v[102:103], v[30:31], v[58:59] op_sel:[0,1,0]
	v_pk_fma_f32 v[56:57], v[104:105], v[34:35], v[56:57] op_sel:[0,1,0]
	v_pk_fma_f32 v[54:55], v[102:103], v[34:35], v[54:55] op_sel:[0,1,0]
	v_pk_fma_f32 v[52:53], v[104:105], v[38:39], v[52:53] op_sel:[0,1,0]
	v_pk_fma_f32 v[50:51], v[102:103], v[38:39], v[50:51] op_sel:[0,1,0]
	v_pk_fma_f32 v[48:49], v[104:105], v[78:79], v[48:49] op_sel:[0,1,0]
	v_pk_fma_f32 v[46:47], v[102:103], v[78:79], v[46:47] op_sel:[0,1,0]
	v_pk_fma_f32 v[44:45], v[104:105], v[82:83], v[44:45] op_sel:[0,1,0]
	v_pk_fma_f32 v[42:43], v[102:103], v[82:83], v[42:43] op_sel:[0,1,0]
	global_load_dwordx4 v[102:105], v[196:197], off nt
	v_lshl_add_u64 v[196:197], v[196:197], 0, s[44:45]
	s_waitcnt vmcnt(15)
	v_pk_fma_f32 v[96:97], v[128:129], v[4:5], v[96:97] op_sel_hi:[1,0,1]
	v_pk_fma_f32 v[94:95], v[126:127], v[4:5], v[94:95] op_sel_hi:[1,0,1]
	v_pk_fma_f32 v[92:93], v[128:129], v[8:9], v[92:93] op_sel_hi:[1,0,1]
	v_pk_fma_f32 v[90:91], v[126:127], v[8:9], v[90:91] op_sel_hi:[1,0,1]
	v_pk_fma_f32 v[88:89], v[128:129], v[12:13], v[88:89] op_sel_hi:[1,0,1]
	v_pk_fma_f32 v[86:87], v[126:127], v[12:13], v[86:87] op_sel_hi:[1,0,1]
	v_pk_fma_f32 v[76:77], v[128:129], v[16:17], v[76:77] op_sel_hi:[1,0,1]
	v_pk_fma_f32 v[74:75], v[126:127], v[16:17], v[74:75] op_sel_hi:[1,0,1]
	v_pk_fma_f32 v[72:73], v[128:129], v[20:21], v[72:73] op_sel_hi:[1,0,1]
	v_pk_fma_f32 v[70:71], v[126:127], v[20:21], v[70:71] op_sel_hi:[1,0,1]
	v_pk_fma_f32 v[68:69], v[128:129], v[24:25], v[68:69] op_sel_hi:[1,0,1]
	v_pk_fma_f32 v[66:67], v[126:127], v[24:25], v[66:67] op_sel_hi:[1,0,1]
	v_pk_fma_f32 v[64:65], v[128:129], v[28:29], v[64:65] op_sel_hi:[1,0,1]
	v_pk_fma_f32 v[62:63], v[126:127], v[28:29], v[62:63] op_sel_hi:[1,0,1]
	v_pk_fma_f32 v[60:61], v[128:129], v[32:33], v[60:61] op_sel_hi:[1,0,1]
	v_pk_fma_f32 v[58:59], v[126:127], v[32:33], v[58:59] op_sel_hi:[1,0,1]
	v_pk_fma_f32 v[56:57], v[128:129], v[36:37], v[56:57] op_sel_hi:[1,0,1]
	v_pk_fma_f32 v[54:55], v[126:127], v[36:37], v[54:55] op_sel_hi:[1,0,1]
	v_pk_fma_f32 v[52:53], v[128:129], v[40:41], v[52:53] op_sel_hi:[1,0,1]
	v_pk_fma_f32 v[50:51], v[126:127], v[40:41], v[50:51] op_sel_hi:[1,0,1]
	v_pk_fma_f32 v[48:49], v[128:129], v[80:81], v[48:49] op_sel_hi:[1,0,1]
	v_pk_fma_f32 v[46:47], v[126:127], v[80:81], v[46:47] op_sel_hi:[1,0,1]
	v_pk_fma_f32 v[44:45], v[128:129], v[84:85], v[44:45] op_sel_hi:[1,0,1]
	v_pk_fma_f32 v[42:43], v[126:127], v[84:85], v[42:43] op_sel_hi:[1,0,1]
	global_load_dwordx4 v[126:129], v[196:197], off nt
	v_lshl_add_u64 v[196:197], v[196:197], 0, s[44:45]
	s_waitcnt vmcnt(15)
	v_pk_fma_f32 v[96:97], v[132:133], v[4:5], v[96:97] op_sel:[0,1,0]
	v_pk_fma_f32 v[94:95], v[130:131], v[4:5], v[94:95] op_sel:[0,1,0]
	v_pk_fma_f32 v[92:93], v[132:133], v[8:9], v[92:93] op_sel:[0,1,0]
	v_pk_fma_f32 v[90:91], v[130:131], v[8:9], v[90:91] op_sel:[0,1,0]
	v_pk_fma_f32 v[88:89], v[132:133], v[12:13], v[88:89] op_sel:[0,1,0]
	v_pk_fma_f32 v[86:87], v[130:131], v[12:13], v[86:87] op_sel:[0,1,0]
	v_pk_fma_f32 v[76:77], v[132:133], v[16:17], v[76:77] op_sel:[0,1,0]
	v_pk_fma_f32 v[74:75], v[130:131], v[16:17], v[74:75] op_sel:[0,1,0]
	v_pk_fma_f32 v[72:73], v[132:133], v[20:21], v[72:73] op_sel:[0,1,0]
	v_pk_fma_f32 v[70:71], v[130:131], v[20:21], v[70:71] op_sel:[0,1,0]
	v_pk_fma_f32 v[68:69], v[132:133], v[24:25], v[68:69] op_sel:[0,1,0]
	v_pk_fma_f32 v[66:67], v[130:131], v[24:25], v[66:67] op_sel:[0,1,0]
	v_pk_fma_f32 v[64:65], v[132:133], v[28:29], v[64:65] op_sel:[0,1,0]
	v_pk_fma_f32 v[62:63], v[130:131], v[28:29], v[62:63] op_sel:[0,1,0]
	v_pk_fma_f32 v[60:61], v[132:133], v[32:33], v[60:61] op_sel:[0,1,0]
	v_pk_fma_f32 v[58:59], v[130:131], v[32:33], v[58:59] op_sel:[0,1,0]
	v_pk_fma_f32 v[56:57], v[132:133], v[36:37], v[56:57] op_sel:[0,1,0]
	v_pk_fma_f32 v[54:55], v[130:131], v[36:37], v[54:55] op_sel:[0,1,0]
	v_pk_fma_f32 v[52:53], v[132:133], v[40:41], v[52:53] op_sel:[0,1,0]
	v_pk_fma_f32 v[50:51], v[130:131], v[40:41], v[50:51] op_sel:[0,1,0]
	v_pk_fma_f32 v[48:49], v[132:133], v[80:81], v[48:49] op_sel:[0,1,0]
	v_pk_fma_f32 v[46:47], v[130:131], v[80:81], v[46:47] op_sel:[0,1,0]
	v_pk_fma_f32 v[44:45], v[132:133], v[84:85], v[44:45] op_sel:[0,1,0]
	v_pk_fma_f32 v[42:43], v[130:131], v[84:85], v[42:43] op_sel:[0,1,0]
	global_load_dwordx4 v[130:133], v[196:197], off nt
	v_lshl_add_u64 v[196:197], v[196:197], 0, s[44:45]
	ds_read_b128 v[2:5], v124 offset:16
	ds_read_b128 v[6:9], v124 offset:1040
	ds_read_b128 v[10:13], v124 offset:2064
	ds_read_b128 v[14:17], v124 offset:3088
	ds_read_b128 v[18:21], v124 offset:4112
	ds_read_b128 v[22:25], v124 offset:5136
	ds_read_b128 v[26:29], v124 offset:6160
	ds_read_b128 v[30:33], v124 offset:7184
	ds_read_b128 v[34:37], v124 offset:8208
	ds_read_b128 v[38:41], v124 offset:9232
	ds_read_b128 v[78:81], v124 offset:10256
	ds_read_b128 v[82:85], v124 offset:11280
	s_waitcnt vmcnt(15) lgkmcnt(0)
	v_pk_fma_f32 v[96:97], v[136:137], v[2:3], v[96:97] op_sel_hi:[1,0,1]
	v_pk_fma_f32 v[94:95], v[134:135], v[2:3], v[94:95] op_sel_hi:[1,0,1]
	v_pk_fma_f32 v[92:93], v[136:137], v[6:7], v[92:93] op_sel_hi:[1,0,1]
	v_pk_fma_f32 v[90:91], v[134:135], v[6:7], v[90:91] op_sel_hi:[1,0,1]
	v_pk_fma_f32 v[88:89], v[136:137], v[10:11], v[88:89] op_sel_hi:[1,0,1]
	v_pk_fma_f32 v[86:87], v[134:135], v[10:11], v[86:87] op_sel_hi:[1,0,1]
	v_pk_fma_f32 v[76:77], v[136:137], v[14:15], v[76:77] op_sel_hi:[1,0,1]
	v_pk_fma_f32 v[74:75], v[134:135], v[14:15], v[74:75] op_sel_hi:[1,0,1]
	v_pk_fma_f32 v[72:73], v[136:137], v[18:19], v[72:73] op_sel_hi:[1,0,1]
	v_pk_fma_f32 v[70:71], v[134:135], v[18:19], v[70:71] op_sel_hi:[1,0,1]
	v_pk_fma_f32 v[68:69], v[136:137], v[22:23], v[68:69] op_sel_hi:[1,0,1]
	v_pk_fma_f32 v[66:67], v[134:135], v[22:23], v[66:67] op_sel_hi:[1,0,1]
	v_pk_fma_f32 v[64:65], v[136:137], v[26:27], v[64:65] op_sel_hi:[1,0,1]
	v_pk_fma_f32 v[62:63], v[134:135], v[26:27], v[62:63] op_sel_hi:[1,0,1]
	v_pk_fma_f32 v[60:61], v[136:137], v[30:31], v[60:61] op_sel_hi:[1,0,1]
	v_pk_fma_f32 v[58:59], v[134:135], v[30:31], v[58:59] op_sel_hi:[1,0,1]
	v_pk_fma_f32 v[56:57], v[136:137], v[34:35], v[56:57] op_sel_hi:[1,0,1]
	v_pk_fma_f32 v[54:55], v[134:135], v[34:35], v[54:55] op_sel_hi:[1,0,1]
	v_pk_fma_f32 v[52:53], v[136:137], v[38:39], v[52:53] op_sel_hi:[1,0,1]
	v_pk_fma_f32 v[50:51], v[134:135], v[38:39], v[50:51] op_sel_hi:[1,0,1]
	v_pk_fma_f32 v[48:49], v[136:137], v[78:79], v[48:49] op_sel_hi:[1,0,1]
	v_pk_fma_f32 v[46:47], v[134:135], v[78:79], v[46:47] op_sel_hi:[1,0,1]
	v_pk_fma_f32 v[44:45], v[136:137], v[82:83], v[44:45] op_sel_hi:[1,0,1]
	v_pk_fma_f32 v[42:43], v[134:135], v[82:83], v[42:43] op_sel_hi:[1,0,1]
	global_load_dwordx4 v[134:137], v[196:197], off nt
	v_lshl_add_u64 v[196:197], v[196:197], 0, s[44:45]
	s_waitcnt vmcnt(15)
	v_pk_fma_f32 v[96:97], v[140:141], v[2:3], v[96:97] op_sel:[0,1,0]
	v_pk_fma_f32 v[94:95], v[138:139], v[2:3], v[94:95] op_sel:[0,1,0]
	v_pk_fma_f32 v[92:93], v[140:141], v[6:7], v[92:93] op_sel:[0,1,0]
	v_pk_fma_f32 v[90:91], v[138:139], v[6:7], v[90:91] op_sel:[0,1,0]
	v_pk_fma_f32 v[88:89], v[140:141], v[10:11], v[88:89] op_sel:[0,1,0]
	v_pk_fma_f32 v[86:87], v[138:139], v[10:11], v[86:87] op_sel:[0,1,0]
	v_pk_fma_f32 v[76:77], v[140:141], v[14:15], v[76:77] op_sel:[0,1,0]
	v_pk_fma_f32 v[74:75], v[138:139], v[14:15], v[74:75] op_sel:[0,1,0]
	v_pk_fma_f32 v[72:73], v[140:141], v[18:19], v[72:73] op_sel:[0,1,0]
	v_pk_fma_f32 v[70:71], v[138:139], v[18:19], v[70:71] op_sel:[0,1,0]
	v_pk_fma_f32 v[68:69], v[140:141], v[22:23], v[68:69] op_sel:[0,1,0]
	v_pk_fma_f32 v[66:67], v[138:139], v[22:23], v[66:67] op_sel:[0,1,0]
	v_pk_fma_f32 v[64:65], v[140:141], v[26:27], v[64:65] op_sel:[0,1,0]
	v_pk_fma_f32 v[62:63], v[138:139], v[26:27], v[62:63] op_sel:[0,1,0]
	v_pk_fma_f32 v[60:61], v[140:141], v[30:31], v[60:61] op_sel:[0,1,0]
	v_pk_fma_f32 v[58:59], v[138:139], v[30:31], v[58:59] op_sel:[0,1,0]
	v_pk_fma_f32 v[56:57], v[140:141], v[34:35], v[56:57] op_sel:[0,1,0]
	v_pk_fma_f32 v[54:55], v[138:139], v[34:35], v[54:55] op_sel:[0,1,0]
	v_pk_fma_f32 v[52:53], v[140:141], v[38:39], v[52:53] op_sel:[0,1,0]
	v_pk_fma_f32 v[50:51], v[138:139], v[38:39], v[50:51] op_sel:[0,1,0]
	v_pk_fma_f32 v[48:49], v[140:141], v[78:79], v[48:49] op_sel:[0,1,0]
	v_pk_fma_f32 v[46:47], v[138:139], v[78:79], v[46:47] op_sel:[0,1,0]
	v_pk_fma_f32 v[44:45], v[140:141], v[82:83], v[44:45] op_sel:[0,1,0]
	v_pk_fma_f32 v[42:43], v[138:139], v[82:83], v[42:43] op_sel:[0,1,0]
	global_load_dwordx4 v[138:141], v[196:197], off nt
	v_lshl_add_u64 v[196:197], v[196:197], 0, s[44:45]
	s_waitcnt vmcnt(15)
	v_pk_fma_f32 v[96:97], v[144:145], v[4:5], v[96:97] op_sel_hi:[1,0,1]
	v_pk_fma_f32 v[94:95], v[142:143], v[4:5], v[94:95] op_sel_hi:[1,0,1]
	v_pk_fma_f32 v[92:93], v[144:145], v[8:9], v[92:93] op_sel_hi:[1,0,1]
	v_pk_fma_f32 v[90:91], v[142:143], v[8:9], v[90:91] op_sel_hi:[1,0,1]
	v_pk_fma_f32 v[88:89], v[144:145], v[12:13], v[88:89] op_sel_hi:[1,0,1]
	v_pk_fma_f32 v[86:87], v[142:143], v[12:13], v[86:87] op_sel_hi:[1,0,1]
	v_pk_fma_f32 v[76:77], v[144:145], v[16:17], v[76:77] op_sel_hi:[1,0,1]
	v_pk_fma_f32 v[74:75], v[142:143], v[16:17], v[74:75] op_sel_hi:[1,0,1]
	v_pk_fma_f32 v[72:73], v[144:145], v[20:21], v[72:73] op_sel_hi:[1,0,1]
	v_pk_fma_f32 v[70:71], v[142:143], v[20:21], v[70:71] op_sel_hi:[1,0,1]
	v_pk_fma_f32 v[68:69], v[144:145], v[24:25], v[68:69] op_sel_hi:[1,0,1]
	v_pk_fma_f32 v[66:67], v[142:143], v[24:25], v[66:67] op_sel_hi:[1,0,1]
	v_pk_fma_f32 v[64:65], v[144:145], v[28:29], v[64:65] op_sel_hi:[1,0,1]
	v_pk_fma_f32 v[62:63], v[142:143], v[28:29], v[62:63] op_sel_hi:[1,0,1]
	v_pk_fma_f32 v[60:61], v[144:145], v[32:33], v[60:61] op_sel_hi:[1,0,1]
	v_pk_fma_f32 v[58:59], v[142:143], v[32:33], v[58:59] op_sel_hi:[1,0,1]
	v_pk_fma_f32 v[56:57], v[144:145], v[36:37], v[56:57] op_sel_hi:[1,0,1]
	v_pk_fma_f32 v[54:55], v[142:143], v[36:37], v[54:55] op_sel_hi:[1,0,1]
	v_pk_fma_f32 v[52:53], v[144:145], v[40:41], v[52:53] op_sel_hi:[1,0,1]
	v_pk_fma_f32 v[50:51], v[142:143], v[40:41], v[50:51] op_sel_hi:[1,0,1]
	v_pk_fma_f32 v[48:49], v[144:145], v[80:81], v[48:49] op_sel_hi:[1,0,1]
	v_pk_fma_f32 v[46:47], v[142:143], v[80:81], v[46:47] op_sel_hi:[1,0,1]
	v_pk_fma_f32 v[44:45], v[144:145], v[84:85], v[44:45] op_sel_hi:[1,0,1]
	v_pk_fma_f32 v[42:43], v[142:143], v[84:85], v[42:43] op_sel_hi:[1,0,1]
	global_load_dwordx4 v[142:145], v[196:197], off nt
	v_lshl_add_u64 v[196:197], v[196:197], 0, s[44:45]
	s_waitcnt vmcnt(15)
	v_pk_fma_f32 v[96:97], v[148:149], v[4:5], v[96:97] op_sel:[0,1,0]
	v_pk_fma_f32 v[94:95], v[146:147], v[4:5], v[94:95] op_sel:[0,1,0]
	v_pk_fma_f32 v[92:93], v[148:149], v[8:9], v[92:93] op_sel:[0,1,0]
	v_pk_fma_f32 v[90:91], v[146:147], v[8:9], v[90:91] op_sel:[0,1,0]
	v_pk_fma_f32 v[88:89], v[148:149], v[12:13], v[88:89] op_sel:[0,1,0]
	v_pk_fma_f32 v[86:87], v[146:147], v[12:13], v[86:87] op_sel:[0,1,0]
	v_pk_fma_f32 v[76:77], v[148:149], v[16:17], v[76:77] op_sel:[0,1,0]
	v_pk_fma_f32 v[74:75], v[146:147], v[16:17], v[74:75] op_sel:[0,1,0]
	v_pk_fma_f32 v[72:73], v[148:149], v[20:21], v[72:73] op_sel:[0,1,0]
	v_pk_fma_f32 v[70:71], v[146:147], v[20:21], v[70:71] op_sel:[0,1,0]
	v_pk_fma_f32 v[68:69], v[148:149], v[24:25], v[68:69] op_sel:[0,1,0]
	v_pk_fma_f32 v[66:67], v[146:147], v[24:25], v[66:67] op_sel:[0,1,0]
	v_pk_fma_f32 v[64:65], v[148:149], v[28:29], v[64:65] op_sel:[0,1,0]
	v_pk_fma_f32 v[62:63], v[146:147], v[28:29], v[62:63] op_sel:[0,1,0]
	v_pk_fma_f32 v[60:61], v[148:149], v[32:33], v[60:61] op_sel:[0,1,0]
	v_pk_fma_f32 v[58:59], v[146:147], v[32:33], v[58:59] op_sel:[0,1,0]
	v_pk_fma_f32 v[56:57], v[148:149], v[36:37], v[56:57] op_sel:[0,1,0]
	v_pk_fma_f32 v[54:55], v[146:147], v[36:37], v[54:55] op_sel:[0,1,0]
	v_pk_fma_f32 v[52:53], v[148:149], v[40:41], v[52:53] op_sel:[0,1,0]
	v_pk_fma_f32 v[50:51], v[146:147], v[40:41], v[50:51] op_sel:[0,1,0]
	v_pk_fma_f32 v[48:49], v[148:149], v[80:81], v[48:49] op_sel:[0,1,0]
	v_pk_fma_f32 v[46:47], v[146:147], v[80:81], v[46:47] op_sel:[0,1,0]
	v_pk_fma_f32 v[44:45], v[148:149], v[84:85], v[44:45] op_sel:[0,1,0]
	v_pk_fma_f32 v[42:43], v[146:147], v[84:85], v[42:43] op_sel:[0,1,0]
	global_load_dwordx4 v[146:149], v[196:197], off nt
	v_lshl_add_u64 v[196:197], v[196:197], 0, s[44:45]
	ds_read_b128 v[2:5], v124 offset:32
	ds_read_b128 v[6:9], v124 offset:1056
	ds_read_b128 v[10:13], v124 offset:2080
	ds_read_b128 v[14:17], v124 offset:3104
	ds_read_b128 v[18:21], v124 offset:4128
	ds_read_b128 v[22:25], v124 offset:5152
	ds_read_b128 v[26:29], v124 offset:6176
	ds_read_b128 v[30:33], v124 offset:7200
	ds_read_b128 v[34:37], v124 offset:8224
	ds_read_b128 v[38:41], v124 offset:9248
	ds_read_b128 v[78:81], v124 offset:10272
	ds_read_b128 v[82:85], v124 offset:11296
	s_waitcnt vmcnt(15) lgkmcnt(0)
	v_pk_fma_f32 v[96:97], v[152:153], v[2:3], v[96:97] op_sel_hi:[1,0,1]
	v_pk_fma_f32 v[94:95], v[150:151], v[2:3], v[94:95] op_sel_hi:[1,0,1]
	v_pk_fma_f32 v[92:93], v[152:153], v[6:7], v[92:93] op_sel_hi:[1,0,1]
	v_pk_fma_f32 v[90:91], v[150:151], v[6:7], v[90:91] op_sel_hi:[1,0,1]
	v_pk_fma_f32 v[88:89], v[152:153], v[10:11], v[88:89] op_sel_hi:[1,0,1]
	v_pk_fma_f32 v[86:87], v[150:151], v[10:11], v[86:87] op_sel_hi:[1,0,1]
	v_pk_fma_f32 v[76:77], v[152:153], v[14:15], v[76:77] op_sel_hi:[1,0,1]
	v_pk_fma_f32 v[74:75], v[150:151], v[14:15], v[74:75] op_sel_hi:[1,0,1]
	v_pk_fma_f32 v[72:73], v[152:153], v[18:19], v[72:73] op_sel_hi:[1,0,1]
	v_pk_fma_f32 v[70:71], v[150:151], v[18:19], v[70:71] op_sel_hi:[1,0,1]
	v_pk_fma_f32 v[68:69], v[152:153], v[22:23], v[68:69] op_sel_hi:[1,0,1]
	v_pk_fma_f32 v[66:67], v[150:151], v[22:23], v[66:67] op_sel_hi:[1,0,1]
	v_pk_fma_f32 v[64:65], v[152:153], v[26:27], v[64:65] op_sel_hi:[1,0,1]
	v_pk_fma_f32 v[62:63], v[150:151], v[26:27], v[62:63] op_sel_hi:[1,0,1]
	v_pk_fma_f32 v[60:61], v[152:153], v[30:31], v[60:61] op_sel_hi:[1,0,1]
	v_pk_fma_f32 v[58:59], v[150:151], v[30:31], v[58:59] op_sel_hi:[1,0,1]
	v_pk_fma_f32 v[56:57], v[152:153], v[34:35], v[56:57] op_sel_hi:[1,0,1]
	v_pk_fma_f32 v[54:55], v[150:151], v[34:35], v[54:55] op_sel_hi:[1,0,1]
	v_pk_fma_f32 v[52:53], v[152:153], v[38:39], v[52:53] op_sel_hi:[1,0,1]
	v_pk_fma_f32 v[50:51], v[150:151], v[38:39], v[50:51] op_sel_hi:[1,0,1]
	v_pk_fma_f32 v[48:49], v[152:153], v[78:79], v[48:49] op_sel_hi:[1,0,1]
	v_pk_fma_f32 v[46:47], v[150:151], v[78:79], v[46:47] op_sel_hi:[1,0,1]
	v_pk_fma_f32 v[44:45], v[152:153], v[82:83], v[44:45] op_sel_hi:[1,0,1]
	v_pk_fma_f32 v[42:43], v[150:151], v[82:83], v[42:43] op_sel_hi:[1,0,1]
	global_load_dwordx4 v[150:153], v[196:197], off nt
	v_lshl_add_u64 v[196:197], v[196:197], 0, s[44:45]
	s_waitcnt vmcnt(15)
	v_pk_fma_f32 v[96:97], v[170:171], v[2:3], v[96:97] op_sel:[0,1,0]
	v_pk_fma_f32 v[94:95], v[168:169], v[2:3], v[94:95] op_sel:[0,1,0]
	v_pk_fma_f32 v[92:93], v[170:171], v[6:7], v[92:93] op_sel:[0,1,0]
	v_pk_fma_f32 v[90:91], v[168:169], v[6:7], v[90:91] op_sel:[0,1,0]
	v_pk_fma_f32 v[88:89], v[170:171], v[10:11], v[88:89] op_sel:[0,1,0]
	v_pk_fma_f32 v[86:87], v[168:169], v[10:11], v[86:87] op_sel:[0,1,0]
	v_pk_fma_f32 v[76:77], v[170:171], v[14:15], v[76:77] op_sel:[0,1,0]
	v_pk_fma_f32 v[74:75], v[168:169], v[14:15], v[74:75] op_sel:[0,1,0]
	v_pk_fma_f32 v[72:73], v[170:171], v[18:19], v[72:73] op_sel:[0,1,0]
	v_pk_fma_f32 v[70:71], v[168:169], v[18:19], v[70:71] op_sel:[0,1,0]
	v_pk_fma_f32 v[68:69], v[170:171], v[22:23], v[68:69] op_sel:[0,1,0]
	v_pk_fma_f32 v[66:67], v[168:169], v[22:23], v[66:67] op_sel:[0,1,0]
	v_pk_fma_f32 v[64:65], v[170:171], v[26:27], v[64:65] op_sel:[0,1,0]
	v_pk_fma_f32 v[62:63], v[168:169], v[26:27], v[62:63] op_sel:[0,1,0]
	v_pk_fma_f32 v[60:61], v[170:171], v[30:31], v[60:61] op_sel:[0,1,0]
	v_pk_fma_f32 v[58:59], v[168:169], v[30:31], v[58:59] op_sel:[0,1,0]
	v_pk_fma_f32 v[56:57], v[170:171], v[34:35], v[56:57] op_sel:[0,1,0]
	v_pk_fma_f32 v[54:55], v[168:169], v[34:35], v[54:55] op_sel:[0,1,0]
	v_pk_fma_f32 v[52:53], v[170:171], v[38:39], v[52:53] op_sel:[0,1,0]
	v_pk_fma_f32 v[50:51], v[168:169], v[38:39], v[50:51] op_sel:[0,1,0]
	v_pk_fma_f32 v[48:49], v[170:171], v[78:79], v[48:49] op_sel:[0,1,0]
	v_pk_fma_f32 v[46:47], v[168:169], v[78:79], v[46:47] op_sel:[0,1,0]
	v_pk_fma_f32 v[44:45], v[170:171], v[82:83], v[44:45] op_sel:[0,1,0]
	v_pk_fma_f32 v[42:43], v[168:169], v[82:83], v[42:43] op_sel:[0,1,0]
	global_load_dwordx4 v[168:171], v[196:197], off nt
	v_lshl_add_u64 v[196:197], v[196:197], 0, s[44:45]
	s_waitcnt vmcnt(15)
	v_pk_fma_f32 v[96:97], v[174:175], v[4:5], v[96:97] op_sel_hi:[1,0,1]
	v_pk_fma_f32 v[94:95], v[172:173], v[4:5], v[94:95] op_sel_hi:[1,0,1]
	v_pk_fma_f32 v[92:93], v[174:175], v[8:9], v[92:93] op_sel_hi:[1,0,1]
	v_pk_fma_f32 v[90:91], v[172:173], v[8:9], v[90:91] op_sel_hi:[1,0,1]
	v_pk_fma_f32 v[88:89], v[174:175], v[12:13], v[88:89] op_sel_hi:[1,0,1]
	v_pk_fma_f32 v[86:87], v[172:173], v[12:13], v[86:87] op_sel_hi:[1,0,1]
	v_pk_fma_f32 v[76:77], v[174:175], v[16:17], v[76:77] op_sel_hi:[1,0,1]
	v_pk_fma_f32 v[74:75], v[172:173], v[16:17], v[74:75] op_sel_hi:[1,0,1]
	v_pk_fma_f32 v[72:73], v[174:175], v[20:21], v[72:73] op_sel_hi:[1,0,1]
	v_pk_fma_f32 v[70:71], v[172:173], v[20:21], v[70:71] op_sel_hi:[1,0,1]
	v_pk_fma_f32 v[68:69], v[174:175], v[24:25], v[68:69] op_sel_hi:[1,0,1]
	v_pk_fma_f32 v[66:67], v[172:173], v[24:25], v[66:67] op_sel_hi:[1,0,1]
	v_pk_fma_f32 v[64:65], v[174:175], v[28:29], v[64:65] op_sel_hi:[1,0,1]
	v_pk_fma_f32 v[62:63], v[172:173], v[28:29], v[62:63] op_sel_hi:[1,0,1]
	v_pk_fma_f32 v[60:61], v[174:175], v[32:33], v[60:61] op_sel_hi:[1,0,1]
	v_pk_fma_f32 v[58:59], v[172:173], v[32:33], v[58:59] op_sel_hi:[1,0,1]
	v_pk_fma_f32 v[56:57], v[174:175], v[36:37], v[56:57] op_sel_hi:[1,0,1]
	v_pk_fma_f32 v[54:55], v[172:173], v[36:37], v[54:55] op_sel_hi:[1,0,1]
	v_pk_fma_f32 v[52:53], v[174:175], v[40:41], v[52:53] op_sel_hi:[1,0,1]
	v_pk_fma_f32 v[50:51], v[172:173], v[40:41], v[50:51] op_sel_hi:[1,0,1]
	v_pk_fma_f32 v[48:49], v[174:175], v[80:81], v[48:49] op_sel_hi:[1,0,1]
	v_pk_fma_f32 v[46:47], v[172:173], v[80:81], v[46:47] op_sel_hi:[1,0,1]
	v_pk_fma_f32 v[44:45], v[174:175], v[84:85], v[44:45] op_sel_hi:[1,0,1]
	v_pk_fma_f32 v[42:43], v[172:173], v[84:85], v[42:43] op_sel_hi:[1,0,1]
	global_load_dwordx4 v[172:175], v[196:197], off nt
	v_lshl_add_u64 v[196:197], v[196:197], 0, s[44:45]
	s_waitcnt vmcnt(15)
	v_pk_fma_f32 v[96:97], v[178:179], v[4:5], v[96:97] op_sel:[0,1,0]
	v_pk_fma_f32 v[94:95], v[176:177], v[4:5], v[94:95] op_sel:[0,1,0]
	v_pk_fma_f32 v[92:93], v[178:179], v[8:9], v[92:93] op_sel:[0,1,0]
	v_pk_fma_f32 v[90:91], v[176:177], v[8:9], v[90:91] op_sel:[0,1,0]
	v_pk_fma_f32 v[88:89], v[178:179], v[12:13], v[88:89] op_sel:[0,1,0]
	v_pk_fma_f32 v[86:87], v[176:177], v[12:13], v[86:87] op_sel:[0,1,0]
	v_pk_fma_f32 v[76:77], v[178:179], v[16:17], v[76:77] op_sel:[0,1,0]
	v_pk_fma_f32 v[74:75], v[176:177], v[16:17], v[74:75] op_sel:[0,1,0]
	v_pk_fma_f32 v[72:73], v[178:179], v[20:21], v[72:73] op_sel:[0,1,0]
	v_pk_fma_f32 v[70:71], v[176:177], v[20:21], v[70:71] op_sel:[0,1,0]
	v_pk_fma_f32 v[68:69], v[178:179], v[24:25], v[68:69] op_sel:[0,1,0]
	v_pk_fma_f32 v[66:67], v[176:177], v[24:25], v[66:67] op_sel:[0,1,0]
	v_pk_fma_f32 v[64:65], v[178:179], v[28:29], v[64:65] op_sel:[0,1,0]
	v_pk_fma_f32 v[62:63], v[176:177], v[28:29], v[62:63] op_sel:[0,1,0]
	v_pk_fma_f32 v[60:61], v[178:179], v[32:33], v[60:61] op_sel:[0,1,0]
	v_pk_fma_f32 v[58:59], v[176:177], v[32:33], v[58:59] op_sel:[0,1,0]
	v_pk_fma_f32 v[56:57], v[178:179], v[36:37], v[56:57] op_sel:[0,1,0]
	v_pk_fma_f32 v[54:55], v[176:177], v[36:37], v[54:55] op_sel:[0,1,0]
	v_pk_fma_f32 v[52:53], v[178:179], v[40:41], v[52:53] op_sel:[0,1,0]
	v_pk_fma_f32 v[50:51], v[176:177], v[40:41], v[50:51] op_sel:[0,1,0]
	v_pk_fma_f32 v[48:49], v[178:179], v[80:81], v[48:49] op_sel:[0,1,0]
	v_pk_fma_f32 v[46:47], v[176:177], v[80:81], v[46:47] op_sel:[0,1,0]
	v_pk_fma_f32 v[44:45], v[178:179], v[84:85], v[44:45] op_sel:[0,1,0]
	v_pk_fma_f32 v[42:43], v[176:177], v[84:85], v[42:43] op_sel:[0,1,0]
	global_load_dwordx4 v[176:179], v[196:197], off nt
	v_lshl_add_u64 v[196:197], v[196:197], 0, s[44:45]
	ds_read_b128 v[2:5], v124 offset:48
	ds_read_b128 v[6:9], v124 offset:1072
	ds_read_b128 v[10:13], v124 offset:2096
	ds_read_b128 v[14:17], v124 offset:3120
	ds_read_b128 v[18:21], v124 offset:4144
	ds_read_b128 v[22:25], v124 offset:5168
	ds_read_b128 v[26:29], v124 offset:6192
	ds_read_b128 v[30:33], v124 offset:7216
	ds_read_b128 v[34:37], v124 offset:8240
	ds_read_b128 v[38:41], v124 offset:9264
	ds_read_b128 v[78:81], v124 offset:10288
	ds_read_b128 v[82:85], v124 offset:11312
	s_waitcnt vmcnt(15) lgkmcnt(0)
	v_pk_fma_f32 v[96:97], v[182:183], v[2:3], v[96:97] op_sel_hi:[1,0,1]
	v_pk_fma_f32 v[94:95], v[180:181], v[2:3], v[94:95] op_sel_hi:[1,0,1]
	v_pk_fma_f32 v[92:93], v[182:183], v[6:7], v[92:93] op_sel_hi:[1,0,1]
	v_pk_fma_f32 v[90:91], v[180:181], v[6:7], v[90:91] op_sel_hi:[1,0,1]
	v_pk_fma_f32 v[88:89], v[182:183], v[10:11], v[88:89] op_sel_hi:[1,0,1]
	v_pk_fma_f32 v[86:87], v[180:181], v[10:11], v[86:87] op_sel_hi:[1,0,1]
	v_pk_fma_f32 v[76:77], v[182:183], v[14:15], v[76:77] op_sel_hi:[1,0,1]
	v_pk_fma_f32 v[74:75], v[180:181], v[14:15], v[74:75] op_sel_hi:[1,0,1]
	v_pk_fma_f32 v[72:73], v[182:183], v[18:19], v[72:73] op_sel_hi:[1,0,1]
	v_pk_fma_f32 v[70:71], v[180:181], v[18:19], v[70:71] op_sel_hi:[1,0,1]
	v_pk_fma_f32 v[68:69], v[182:183], v[22:23], v[68:69] op_sel_hi:[1,0,1]
	v_pk_fma_f32 v[66:67], v[180:181], v[22:23], v[66:67] op_sel_hi:[1,0,1]
	v_pk_fma_f32 v[64:65], v[182:183], v[26:27], v[64:65] op_sel_hi:[1,0,1]
	v_pk_fma_f32 v[62:63], v[180:181], v[26:27], v[62:63] op_sel_hi:[1,0,1]
	v_pk_fma_f32 v[60:61], v[182:183], v[30:31], v[60:61] op_sel_hi:[1,0,1]
	v_pk_fma_f32 v[58:59], v[180:181], v[30:31], v[58:59] op_sel_hi:[1,0,1]
	v_pk_fma_f32 v[56:57], v[182:183], v[34:35], v[56:57] op_sel_hi:[1,0,1]
	v_pk_fma_f32 v[54:55], v[180:181], v[34:35], v[54:55] op_sel_hi:[1,0,1]
	v_pk_fma_f32 v[52:53], v[182:183], v[38:39], v[52:53] op_sel_hi:[1,0,1]
	v_pk_fma_f32 v[50:51], v[180:181], v[38:39], v[50:51] op_sel_hi:[1,0,1]
	v_pk_fma_f32 v[48:49], v[182:183], v[78:79], v[48:49] op_sel_hi:[1,0,1]
	v_pk_fma_f32 v[46:47], v[180:181], v[78:79], v[46:47] op_sel_hi:[1,0,1]
	v_pk_fma_f32 v[44:45], v[182:183], v[82:83], v[44:45] op_sel_hi:[1,0,1]
	v_pk_fma_f32 v[42:43], v[180:181], v[82:83], v[42:43] op_sel_hi:[1,0,1]
	global_load_dwordx4 v[180:183], v[196:197], off nt
	v_lshl_add_u64 v[196:197], v[196:197], 0, s[44:45]
	s_waitcnt vmcnt(15)
	v_pk_fma_f32 v[96:97], v[186:187], v[2:3], v[96:97] op_sel:[0,1,0]
	v_pk_fma_f32 v[94:95], v[184:185], v[2:3], v[94:95] op_sel:[0,1,0]
	v_pk_fma_f32 v[92:93], v[186:187], v[6:7], v[92:93] op_sel:[0,1,0]
	v_pk_fma_f32 v[90:91], v[184:185], v[6:7], v[90:91] op_sel:[0,1,0]
	v_pk_fma_f32 v[88:89], v[186:187], v[10:11], v[88:89] op_sel:[0,1,0]
	v_pk_fma_f32 v[86:87], v[184:185], v[10:11], v[86:87] op_sel:[0,1,0]
	v_pk_fma_f32 v[76:77], v[186:187], v[14:15], v[76:77] op_sel:[0,1,0]
	v_pk_fma_f32 v[74:75], v[184:185], v[14:15], v[74:75] op_sel:[0,1,0]
	v_pk_fma_f32 v[72:73], v[186:187], v[18:19], v[72:73] op_sel:[0,1,0]
	v_pk_fma_f32 v[70:71], v[184:185], v[18:19], v[70:71] op_sel:[0,1,0]
	v_pk_fma_f32 v[68:69], v[186:187], v[22:23], v[68:69] op_sel:[0,1,0]
	v_pk_fma_f32 v[66:67], v[184:185], v[22:23], v[66:67] op_sel:[0,1,0]
	v_pk_fma_f32 v[64:65], v[186:187], v[26:27], v[64:65] op_sel:[0,1,0]
	v_pk_fma_f32 v[62:63], v[184:185], v[26:27], v[62:63] op_sel:[0,1,0]
	v_pk_fma_f32 v[60:61], v[186:187], v[30:31], v[60:61] op_sel:[0,1,0]
	v_pk_fma_f32 v[58:59], v[184:185], v[30:31], v[58:59] op_sel:[0,1,0]
	v_pk_fma_f32 v[56:57], v[186:187], v[34:35], v[56:57] op_sel:[0,1,0]
	v_pk_fma_f32 v[54:55], v[184:185], v[34:35], v[54:55] op_sel:[0,1,0]
	v_pk_fma_f32 v[52:53], v[186:187], v[38:39], v[52:53] op_sel:[0,1,0]
	v_pk_fma_f32 v[50:51], v[184:185], v[38:39], v[50:51] op_sel:[0,1,0]
	v_pk_fma_f32 v[48:49], v[186:187], v[78:79], v[48:49] op_sel:[0,1,0]
	v_pk_fma_f32 v[46:47], v[184:185], v[78:79], v[46:47] op_sel:[0,1,0]
	v_pk_fma_f32 v[44:45], v[186:187], v[82:83], v[44:45] op_sel:[0,1,0]
	v_pk_fma_f32 v[42:43], v[184:185], v[82:83], v[42:43] op_sel:[0,1,0]
	global_load_dwordx4 v[184:187], v[196:197], off nt
	v_lshl_add_u64 v[196:197], v[196:197], 0, s[44:45]
	s_waitcnt vmcnt(15)
	v_pk_fma_f32 v[96:97], v[190:191], v[4:5], v[96:97] op_sel_hi:[1,0,1]
	v_pk_fma_f32 v[94:95], v[188:189], v[4:5], v[94:95] op_sel_hi:[1,0,1]
	v_pk_fma_f32 v[92:93], v[190:191], v[8:9], v[92:93] op_sel_hi:[1,0,1]
	v_pk_fma_f32 v[90:91], v[188:189], v[8:9], v[90:91] op_sel_hi:[1,0,1]
	v_pk_fma_f32 v[88:89], v[190:191], v[12:13], v[88:89] op_sel_hi:[1,0,1]
	v_pk_fma_f32 v[86:87], v[188:189], v[12:13], v[86:87] op_sel_hi:[1,0,1]
	v_pk_fma_f32 v[76:77], v[190:191], v[16:17], v[76:77] op_sel_hi:[1,0,1]
	v_pk_fma_f32 v[74:75], v[188:189], v[16:17], v[74:75] op_sel_hi:[1,0,1]
	v_pk_fma_f32 v[72:73], v[190:191], v[20:21], v[72:73] op_sel_hi:[1,0,1]
	v_pk_fma_f32 v[70:71], v[188:189], v[20:21], v[70:71] op_sel_hi:[1,0,1]
	v_pk_fma_f32 v[68:69], v[190:191], v[24:25], v[68:69] op_sel_hi:[1,0,1]
	v_pk_fma_f32 v[66:67], v[188:189], v[24:25], v[66:67] op_sel_hi:[1,0,1]
	v_pk_fma_f32 v[64:65], v[190:191], v[28:29], v[64:65] op_sel_hi:[1,0,1]
	v_pk_fma_f32 v[62:63], v[188:189], v[28:29], v[62:63] op_sel_hi:[1,0,1]
	v_pk_fma_f32 v[60:61], v[190:191], v[32:33], v[60:61] op_sel_hi:[1,0,1]
	v_pk_fma_f32 v[58:59], v[188:189], v[32:33], v[58:59] op_sel_hi:[1,0,1]
	v_pk_fma_f32 v[56:57], v[190:191], v[36:37], v[56:57] op_sel_hi:[1,0,1]
	v_pk_fma_f32 v[54:55], v[188:189], v[36:37], v[54:55] op_sel_hi:[1,0,1]
	v_pk_fma_f32 v[52:53], v[190:191], v[40:41], v[52:53] op_sel_hi:[1,0,1]
	v_pk_fma_f32 v[50:51], v[188:189], v[40:41], v[50:51] op_sel_hi:[1,0,1]
	v_pk_fma_f32 v[48:49], v[190:191], v[80:81], v[48:49] op_sel_hi:[1,0,1]
	v_pk_fma_f32 v[46:47], v[188:189], v[80:81], v[46:47] op_sel_hi:[1,0,1]
	v_pk_fma_f32 v[44:45], v[190:191], v[84:85], v[44:45] op_sel_hi:[1,0,1]
	v_pk_fma_f32 v[42:43], v[188:189], v[84:85], v[42:43] op_sel_hi:[1,0,1]
	global_load_dwordx4 v[188:191], v[196:197], off nt
	v_lshl_add_u64 v[196:197], v[196:197], 0, s[44:45]
	s_waitcnt vmcnt(15)
	v_pk_fma_f32 v[96:97], v[194:195], v[4:5], v[96:97] op_sel:[0,1,0]
	v_pk_fma_f32 v[94:95], v[192:193], v[4:5], v[94:95] op_sel:[0,1,0]
	v_pk_fma_f32 v[92:93], v[194:195], v[8:9], v[92:93] op_sel:[0,1,0]
	v_pk_fma_f32 v[90:91], v[192:193], v[8:9], v[90:91] op_sel:[0,1,0]
	v_pk_fma_f32 v[88:89], v[194:195], v[12:13], v[88:89] op_sel:[0,1,0]
	v_pk_fma_f32 v[86:87], v[192:193], v[12:13], v[86:87] op_sel:[0,1,0]
	v_pk_fma_f32 v[76:77], v[194:195], v[16:17], v[76:77] op_sel:[0,1,0]
	v_pk_fma_f32 v[74:75], v[192:193], v[16:17], v[74:75] op_sel:[0,1,0]
	v_pk_fma_f32 v[72:73], v[194:195], v[20:21], v[72:73] op_sel:[0,1,0]
	v_pk_fma_f32 v[70:71], v[192:193], v[20:21], v[70:71] op_sel:[0,1,0]
	v_pk_fma_f32 v[68:69], v[194:195], v[24:25], v[68:69] op_sel:[0,1,0]
	v_pk_fma_f32 v[66:67], v[192:193], v[24:25], v[66:67] op_sel:[0,1,0]
	v_pk_fma_f32 v[64:65], v[194:195], v[28:29], v[64:65] op_sel:[0,1,0]
	v_pk_fma_f32 v[62:63], v[192:193], v[28:29], v[62:63] op_sel:[0,1,0]
	v_pk_fma_f32 v[60:61], v[194:195], v[32:33], v[60:61] op_sel:[0,1,0]
	v_pk_fma_f32 v[58:59], v[192:193], v[32:33], v[58:59] op_sel:[0,1,0]
	v_pk_fma_f32 v[56:57], v[194:195], v[36:37], v[56:57] op_sel:[0,1,0]
	v_pk_fma_f32 v[54:55], v[192:193], v[36:37], v[54:55] op_sel:[0,1,0]
	v_pk_fma_f32 v[52:53], v[194:195], v[40:41], v[52:53] op_sel:[0,1,0]
	v_pk_fma_f32 v[50:51], v[192:193], v[40:41], v[50:51] op_sel:[0,1,0]
	v_pk_fma_f32 v[48:49], v[194:195], v[80:81], v[48:49] op_sel:[0,1,0]
	v_pk_fma_f32 v[46:47], v[192:193], v[80:81], v[46:47] op_sel:[0,1,0]
	v_pk_fma_f32 v[44:45], v[194:195], v[84:85], v[44:45] op_sel:[0,1,0]
	v_pk_fma_f32 v[42:43], v[192:193], v[84:85], v[42:43] op_sel:[0,1,0]
	global_load_dwordx4 v[192:195], v[196:197], off nt
	ds_read_b128 v[2:5], v124 offset:64
	ds_read_b128 v[6:9], v124 offset:1088
	ds_read_b128 v[10:13], v124 offset:2112
	ds_read_b128 v[14:17], v124 offset:3136
	ds_read_b128 v[18:21], v124 offset:4160
	ds_read_b128 v[22:25], v124 offset:5184
	ds_read_b128 v[26:29], v124 offset:6208
	ds_read_b128 v[30:33], v124 offset:7232
	ds_read_b128 v[34:37], v124 offset:8256
	ds_read_b128 v[38:41], v124 offset:9280
	ds_read_b128 v[78:81], v124 offset:10304
	ds_read_b128 v[82:85], v124 offset:11328
	s_waitcnt vmcnt(15) lgkmcnt(0)
	v_pk_fma_f32 v[96:97], v[100:101], v[2:3], v[96:97] op_sel_hi:[1,0,1]
	v_pk_fma_f32 v[94:95], v[98:99], v[2:3], v[94:95] op_sel_hi:[1,0,1]
	v_pk_fma_f32 v[92:93], v[100:101], v[6:7], v[92:93] op_sel_hi:[1,0,1]
	v_pk_fma_f32 v[90:91], v[98:99], v[6:7], v[90:91] op_sel_hi:[1,0,1]
	v_pk_fma_f32 v[88:89], v[100:101], v[10:11], v[88:89] op_sel_hi:[1,0,1]
	v_pk_fma_f32 v[86:87], v[98:99], v[10:11], v[86:87] op_sel_hi:[1,0,1]
	v_pk_fma_f32 v[76:77], v[100:101], v[14:15], v[76:77] op_sel_hi:[1,0,1]
	v_pk_fma_f32 v[74:75], v[98:99], v[14:15], v[74:75] op_sel_hi:[1,0,1]
	v_pk_fma_f32 v[72:73], v[100:101], v[18:19], v[72:73] op_sel_hi:[1,0,1]
	v_pk_fma_f32 v[70:71], v[98:99], v[18:19], v[70:71] op_sel_hi:[1,0,1]
	v_pk_fma_f32 v[68:69], v[100:101], v[22:23], v[68:69] op_sel_hi:[1,0,1]
	v_pk_fma_f32 v[66:67], v[98:99], v[22:23], v[66:67] op_sel_hi:[1,0,1]
	v_pk_fma_f32 v[64:65], v[100:101], v[26:27], v[64:65] op_sel_hi:[1,0,1]
	v_pk_fma_f32 v[62:63], v[98:99], v[26:27], v[62:63] op_sel_hi:[1,0,1]
	v_pk_fma_f32 v[60:61], v[100:101], v[30:31], v[60:61] op_sel_hi:[1,0,1]
	v_pk_fma_f32 v[58:59], v[98:99], v[30:31], v[58:59] op_sel_hi:[1,0,1]
	v_pk_fma_f32 v[56:57], v[100:101], v[34:35], v[56:57] op_sel_hi:[1,0,1]
	v_pk_fma_f32 v[54:55], v[98:99], v[34:35], v[54:55] op_sel_hi:[1,0,1]
	v_pk_fma_f32 v[52:53], v[100:101], v[38:39], v[52:53] op_sel_hi:[1,0,1]
	v_pk_fma_f32 v[50:51], v[98:99], v[38:39], v[50:51] op_sel_hi:[1,0,1]
	v_pk_fma_f32 v[48:49], v[100:101], v[78:79], v[48:49] op_sel_hi:[1,0,1]
	v_pk_fma_f32 v[46:47], v[98:99], v[78:79], v[46:47] op_sel_hi:[1,0,1]
	v_pk_fma_f32 v[44:45], v[100:101], v[82:83], v[44:45] op_sel_hi:[1,0,1]
	v_pk_fma_f32 v[42:43], v[98:99], v[82:83], v[42:43] op_sel_hi:[1,0,1]
	s_waitcnt vmcnt(14)
	v_pk_fma_f32 v[96:97], v[104:105], v[2:3], v[96:97] op_sel:[0,1,0]
	v_pk_fma_f32 v[94:95], v[102:103], v[2:3], v[94:95] op_sel:[0,1,0]
	v_pk_fma_f32 v[92:93], v[104:105], v[6:7], v[92:93] op_sel:[0,1,0]
	v_pk_fma_f32 v[90:91], v[102:103], v[6:7], v[90:91] op_sel:[0,1,0]
	v_pk_fma_f32 v[88:89], v[104:105], v[10:11], v[88:89] op_sel:[0,1,0]
	v_pk_fma_f32 v[86:87], v[102:103], v[10:11], v[86:87] op_sel:[0,1,0]
	v_pk_fma_f32 v[76:77], v[104:105], v[14:15], v[76:77] op_sel:[0,1,0]
	v_pk_fma_f32 v[74:75], v[102:103], v[14:15], v[74:75] op_sel:[0,1,0]
	v_pk_fma_f32 v[72:73], v[104:105], v[18:19], v[72:73] op_sel:[0,1,0]
	v_pk_fma_f32 v[70:71], v[102:103], v[18:19], v[70:71] op_sel:[0,1,0]
	v_pk_fma_f32 v[68:69], v[104:105], v[22:23], v[68:69] op_sel:[0,1,0]
	v_pk_fma_f32 v[66:67], v[102:103], v[22:23], v[66:67] op_sel:[0,1,0]
	v_pk_fma_f32 v[64:65], v[104:105], v[26:27], v[64:65] op_sel:[0,1,0]
	v_pk_fma_f32 v[62:63], v[102:103], v[26:27], v[62:63] op_sel:[0,1,0]
	v_pk_fma_f32 v[60:61], v[104:105], v[30:31], v[60:61] op_sel:[0,1,0]
	v_pk_fma_f32 v[58:59], v[102:103], v[30:31], v[58:59] op_sel:[0,1,0]
	v_pk_fma_f32 v[56:57], v[104:105], v[34:35], v[56:57] op_sel:[0,1,0]
	v_pk_fma_f32 v[54:55], v[102:103], v[34:35], v[54:55] op_sel:[0,1,0]
	v_pk_fma_f32 v[52:53], v[104:105], v[38:39], v[52:53] op_sel:[0,1,0]
	v_pk_fma_f32 v[50:51], v[102:103], v[38:39], v[50:51] op_sel:[0,1,0]
	v_pk_fma_f32 v[48:49], v[104:105], v[78:79], v[48:49] op_sel:[0,1,0]
	v_pk_fma_f32 v[46:47], v[102:103], v[78:79], v[46:47] op_sel:[0,1,0]
	v_pk_fma_f32 v[44:45], v[104:105], v[82:83], v[44:45] op_sel:[0,1,0]
	v_pk_fma_f32 v[42:43], v[102:103], v[82:83], v[42:43] op_sel:[0,1,0]
	s_waitcnt vmcnt(13)
	v_pk_fma_f32 v[96:97], v[128:129], v[4:5], v[96:97] op_sel_hi:[1,0,1]
	v_pk_fma_f32 v[94:95], v[126:127], v[4:5], v[94:95] op_sel_hi:[1,0,1]
	v_pk_fma_f32 v[92:93], v[128:129], v[8:9], v[92:93] op_sel_hi:[1,0,1]
	v_pk_fma_f32 v[90:91], v[126:127], v[8:9], v[90:91] op_sel_hi:[1,0,1]
	v_pk_fma_f32 v[88:89], v[128:129], v[12:13], v[88:89] op_sel_hi:[1,0,1]
	v_pk_fma_f32 v[86:87], v[126:127], v[12:13], v[86:87] op_sel_hi:[1,0,1]
	v_pk_fma_f32 v[76:77], v[128:129], v[16:17], v[76:77] op_sel_hi:[1,0,1]
	v_pk_fma_f32 v[74:75], v[126:127], v[16:17], v[74:75] op_sel_hi:[1,0,1]
	v_pk_fma_f32 v[72:73], v[128:129], v[20:21], v[72:73] op_sel_hi:[1,0,1]
	v_pk_fma_f32 v[70:71], v[126:127], v[20:21], v[70:71] op_sel_hi:[1,0,1]
	v_pk_fma_f32 v[68:69], v[128:129], v[24:25], v[68:69] op_sel_hi:[1,0,1]
	v_pk_fma_f32 v[66:67], v[126:127], v[24:25], v[66:67] op_sel_hi:[1,0,1]
	v_pk_fma_f32 v[64:65], v[128:129], v[28:29], v[64:65] op_sel_hi:[1,0,1]
	v_pk_fma_f32 v[62:63], v[126:127], v[28:29], v[62:63] op_sel_hi:[1,0,1]
	v_pk_fma_f32 v[60:61], v[128:129], v[32:33], v[60:61] op_sel_hi:[1,0,1]
	v_pk_fma_f32 v[58:59], v[126:127], v[32:33], v[58:59] op_sel_hi:[1,0,1]
	v_pk_fma_f32 v[56:57], v[128:129], v[36:37], v[56:57] op_sel_hi:[1,0,1]
	v_pk_fma_f32 v[54:55], v[126:127], v[36:37], v[54:55] op_sel_hi:[1,0,1]
	v_pk_fma_f32 v[52:53], v[128:129], v[40:41], v[52:53] op_sel_hi:[1,0,1]
	v_pk_fma_f32 v[50:51], v[126:127], v[40:41], v[50:51] op_sel_hi:[1,0,1]
	v_pk_fma_f32 v[48:49], v[128:129], v[80:81], v[48:49] op_sel_hi:[1,0,1]
	v_pk_fma_f32 v[46:47], v[126:127], v[80:81], v[46:47] op_sel_hi:[1,0,1]
	v_pk_fma_f32 v[44:45], v[128:129], v[84:85], v[44:45] op_sel_hi:[1,0,1]
	v_pk_fma_f32 v[42:43], v[126:127], v[84:85], v[42:43] op_sel_hi:[1,0,1]
	s_waitcnt vmcnt(12)
	v_pk_fma_f32 v[96:97], v[132:133], v[4:5], v[96:97] op_sel:[0,1,0]
	v_pk_fma_f32 v[94:95], v[130:131], v[4:5], v[94:95] op_sel:[0,1,0]
	v_pk_fma_f32 v[92:93], v[132:133], v[8:9], v[92:93] op_sel:[0,1,0]
	v_pk_fma_f32 v[90:91], v[130:131], v[8:9], v[90:91] op_sel:[0,1,0]
	v_pk_fma_f32 v[88:89], v[132:133], v[12:13], v[88:89] op_sel:[0,1,0]
	v_pk_fma_f32 v[86:87], v[130:131], v[12:13], v[86:87] op_sel:[0,1,0]
	v_pk_fma_f32 v[76:77], v[132:133], v[16:17], v[76:77] op_sel:[0,1,0]
	v_pk_fma_f32 v[74:75], v[130:131], v[16:17], v[74:75] op_sel:[0,1,0]
	v_pk_fma_f32 v[72:73], v[132:133], v[20:21], v[72:73] op_sel:[0,1,0]
	v_pk_fma_f32 v[70:71], v[130:131], v[20:21], v[70:71] op_sel:[0,1,0]
	v_pk_fma_f32 v[68:69], v[132:133], v[24:25], v[68:69] op_sel:[0,1,0]
	v_pk_fma_f32 v[66:67], v[130:131], v[24:25], v[66:67] op_sel:[0,1,0]
	v_pk_fma_f32 v[64:65], v[132:133], v[28:29], v[64:65] op_sel:[0,1,0]
	v_pk_fma_f32 v[62:63], v[130:131], v[28:29], v[62:63] op_sel:[0,1,0]
	v_pk_fma_f32 v[60:61], v[132:133], v[32:33], v[60:61] op_sel:[0,1,0]
	v_pk_fma_f32 v[58:59], v[130:131], v[32:33], v[58:59] op_sel:[0,1,0]
	v_pk_fma_f32 v[56:57], v[132:133], v[36:37], v[56:57] op_sel:[0,1,0]
	v_pk_fma_f32 v[54:55], v[130:131], v[36:37], v[54:55] op_sel:[0,1,0]
	v_pk_fma_f32 v[52:53], v[132:133], v[40:41], v[52:53] op_sel:[0,1,0]
	v_pk_fma_f32 v[50:51], v[130:131], v[40:41], v[50:51] op_sel:[0,1,0]
	v_pk_fma_f32 v[48:49], v[132:133], v[80:81], v[48:49] op_sel:[0,1,0]
	v_pk_fma_f32 v[46:47], v[130:131], v[80:81], v[46:47] op_sel:[0,1,0]
	v_pk_fma_f32 v[44:45], v[132:133], v[84:85], v[44:45] op_sel:[0,1,0]
	v_pk_fma_f32 v[42:43], v[130:131], v[84:85], v[42:43] op_sel:[0,1,0]
	ds_read_b128 v[2:5], v124 offset:80
	ds_read_b128 v[6:9], v124 offset:1104
	ds_read_b128 v[10:13], v124 offset:2128
	ds_read_b128 v[14:17], v124 offset:3152
	ds_read_b128 v[18:21], v124 offset:4176
	ds_read_b128 v[22:25], v124 offset:5200
	ds_read_b128 v[26:29], v124 offset:6224
	ds_read_b128 v[30:33], v124 offset:7248
	ds_read_b128 v[34:37], v124 offset:8272
	ds_read_b128 v[38:41], v124 offset:9296
	ds_read_b128 v[78:81], v124 offset:10320
	ds_read_b128 v[82:85], v124 offset:11344
	s_waitcnt vmcnt(11) lgkmcnt(0)
	v_pk_fma_f32 v[96:97], v[136:137], v[2:3], v[96:97] op_sel_hi:[1,0,1]
	v_pk_fma_f32 v[94:95], v[134:135], v[2:3], v[94:95] op_sel_hi:[1,0,1]
	v_pk_fma_f32 v[92:93], v[136:137], v[6:7], v[92:93] op_sel_hi:[1,0,1]
	v_pk_fma_f32 v[90:91], v[134:135], v[6:7], v[90:91] op_sel_hi:[1,0,1]
	v_pk_fma_f32 v[88:89], v[136:137], v[10:11], v[88:89] op_sel_hi:[1,0,1]
	v_pk_fma_f32 v[86:87], v[134:135], v[10:11], v[86:87] op_sel_hi:[1,0,1]
	v_pk_fma_f32 v[76:77], v[136:137], v[14:15], v[76:77] op_sel_hi:[1,0,1]
	v_pk_fma_f32 v[74:75], v[134:135], v[14:15], v[74:75] op_sel_hi:[1,0,1]
	v_pk_fma_f32 v[72:73], v[136:137], v[18:19], v[72:73] op_sel_hi:[1,0,1]
	v_pk_fma_f32 v[70:71], v[134:135], v[18:19], v[70:71] op_sel_hi:[1,0,1]
	v_pk_fma_f32 v[68:69], v[136:137], v[22:23], v[68:69] op_sel_hi:[1,0,1]
	v_pk_fma_f32 v[66:67], v[134:135], v[22:23], v[66:67] op_sel_hi:[1,0,1]
	v_pk_fma_f32 v[64:65], v[136:137], v[26:27], v[64:65] op_sel_hi:[1,0,1]
	v_pk_fma_f32 v[62:63], v[134:135], v[26:27], v[62:63] op_sel_hi:[1,0,1]
	v_pk_fma_f32 v[60:61], v[136:137], v[30:31], v[60:61] op_sel_hi:[1,0,1]
	v_pk_fma_f32 v[58:59], v[134:135], v[30:31], v[58:59] op_sel_hi:[1,0,1]
	v_pk_fma_f32 v[56:57], v[136:137], v[34:35], v[56:57] op_sel_hi:[1,0,1]
	v_pk_fma_f32 v[54:55], v[134:135], v[34:35], v[54:55] op_sel_hi:[1,0,1]
	v_pk_fma_f32 v[52:53], v[136:137], v[38:39], v[52:53] op_sel_hi:[1,0,1]
	v_pk_fma_f32 v[50:51], v[134:135], v[38:39], v[50:51] op_sel_hi:[1,0,1]
	v_pk_fma_f32 v[48:49], v[136:137], v[78:79], v[48:49] op_sel_hi:[1,0,1]
	v_pk_fma_f32 v[46:47], v[134:135], v[78:79], v[46:47] op_sel_hi:[1,0,1]
	v_pk_fma_f32 v[44:45], v[136:137], v[82:83], v[44:45] op_sel_hi:[1,0,1]
	v_pk_fma_f32 v[42:43], v[134:135], v[82:83], v[42:43] op_sel_hi:[1,0,1]
	s_waitcnt vmcnt(10)
	v_pk_fma_f32 v[96:97], v[140:141], v[2:3], v[96:97] op_sel:[0,1,0]
	v_pk_fma_f32 v[94:95], v[138:139], v[2:3], v[94:95] op_sel:[0,1,0]
	v_pk_fma_f32 v[92:93], v[140:141], v[6:7], v[92:93] op_sel:[0,1,0]
	v_pk_fma_f32 v[90:91], v[138:139], v[6:7], v[90:91] op_sel:[0,1,0]
	v_pk_fma_f32 v[88:89], v[140:141], v[10:11], v[88:89] op_sel:[0,1,0]
	v_pk_fma_f32 v[86:87], v[138:139], v[10:11], v[86:87] op_sel:[0,1,0]
	v_pk_fma_f32 v[76:77], v[140:141], v[14:15], v[76:77] op_sel:[0,1,0]
	v_pk_fma_f32 v[74:75], v[138:139], v[14:15], v[74:75] op_sel:[0,1,0]
	v_pk_fma_f32 v[72:73], v[140:141], v[18:19], v[72:73] op_sel:[0,1,0]
	v_pk_fma_f32 v[70:71], v[138:139], v[18:19], v[70:71] op_sel:[0,1,0]
	v_pk_fma_f32 v[68:69], v[140:141], v[22:23], v[68:69] op_sel:[0,1,0]
	v_pk_fma_f32 v[66:67], v[138:139], v[22:23], v[66:67] op_sel:[0,1,0]
	v_pk_fma_f32 v[64:65], v[140:141], v[26:27], v[64:65] op_sel:[0,1,0]
	v_pk_fma_f32 v[62:63], v[138:139], v[26:27], v[62:63] op_sel:[0,1,0]
	v_pk_fma_f32 v[60:61], v[140:141], v[30:31], v[60:61] op_sel:[0,1,0]
	v_pk_fma_f32 v[58:59], v[138:139], v[30:31], v[58:59] op_sel:[0,1,0]
	v_pk_fma_f32 v[56:57], v[140:141], v[34:35], v[56:57] op_sel:[0,1,0]
	v_pk_fma_f32 v[54:55], v[138:139], v[34:35], v[54:55] op_sel:[0,1,0]
	v_pk_fma_f32 v[52:53], v[140:141], v[38:39], v[52:53] op_sel:[0,1,0]
	v_pk_fma_f32 v[50:51], v[138:139], v[38:39], v[50:51] op_sel:[0,1,0]
	v_pk_fma_f32 v[48:49], v[140:141], v[78:79], v[48:49] op_sel:[0,1,0]
	v_pk_fma_f32 v[46:47], v[138:139], v[78:79], v[46:47] op_sel:[0,1,0]
	v_pk_fma_f32 v[44:45], v[140:141], v[82:83], v[44:45] op_sel:[0,1,0]
	v_pk_fma_f32 v[42:43], v[138:139], v[82:83], v[42:43] op_sel:[0,1,0]
	s_waitcnt vmcnt(9)
	v_pk_fma_f32 v[96:97], v[144:145], v[4:5], v[96:97] op_sel_hi:[1,0,1]
	v_pk_fma_f32 v[94:95], v[142:143], v[4:5], v[94:95] op_sel_hi:[1,0,1]
	v_pk_fma_f32 v[92:93], v[144:145], v[8:9], v[92:93] op_sel_hi:[1,0,1]
	v_pk_fma_f32 v[90:91], v[142:143], v[8:9], v[90:91] op_sel_hi:[1,0,1]
	v_pk_fma_f32 v[88:89], v[144:145], v[12:13], v[88:89] op_sel_hi:[1,0,1]
	v_pk_fma_f32 v[86:87], v[142:143], v[12:13], v[86:87] op_sel_hi:[1,0,1]
	v_pk_fma_f32 v[76:77], v[144:145], v[16:17], v[76:77] op_sel_hi:[1,0,1]
	v_pk_fma_f32 v[74:75], v[142:143], v[16:17], v[74:75] op_sel_hi:[1,0,1]
	v_pk_fma_f32 v[72:73], v[144:145], v[20:21], v[72:73] op_sel_hi:[1,0,1]
	v_pk_fma_f32 v[70:71], v[142:143], v[20:21], v[70:71] op_sel_hi:[1,0,1]
	v_pk_fma_f32 v[68:69], v[144:145], v[24:25], v[68:69] op_sel_hi:[1,0,1]
	v_pk_fma_f32 v[66:67], v[142:143], v[24:25], v[66:67] op_sel_hi:[1,0,1]
	v_pk_fma_f32 v[64:65], v[144:145], v[28:29], v[64:65] op_sel_hi:[1,0,1]
	v_pk_fma_f32 v[62:63], v[142:143], v[28:29], v[62:63] op_sel_hi:[1,0,1]
	v_pk_fma_f32 v[60:61], v[144:145], v[32:33], v[60:61] op_sel_hi:[1,0,1]
	v_pk_fma_f32 v[58:59], v[142:143], v[32:33], v[58:59] op_sel_hi:[1,0,1]
	v_pk_fma_f32 v[56:57], v[144:145], v[36:37], v[56:57] op_sel_hi:[1,0,1]
	v_pk_fma_f32 v[54:55], v[142:143], v[36:37], v[54:55] op_sel_hi:[1,0,1]
	v_pk_fma_f32 v[52:53], v[144:145], v[40:41], v[52:53] op_sel_hi:[1,0,1]
	v_pk_fma_f32 v[50:51], v[142:143], v[40:41], v[50:51] op_sel_hi:[1,0,1]
	v_pk_fma_f32 v[48:49], v[144:145], v[80:81], v[48:49] op_sel_hi:[1,0,1]
	v_pk_fma_f32 v[46:47], v[142:143], v[80:81], v[46:47] op_sel_hi:[1,0,1]
	v_pk_fma_f32 v[44:45], v[144:145], v[84:85], v[44:45] op_sel_hi:[1,0,1]
	v_pk_fma_f32 v[42:43], v[142:143], v[84:85], v[42:43] op_sel_hi:[1,0,1]
	s_waitcnt vmcnt(8)
	v_pk_fma_f32 v[96:97], v[148:149], v[4:5], v[96:97] op_sel:[0,1,0]
	v_pk_fma_f32 v[94:95], v[146:147], v[4:5], v[94:95] op_sel:[0,1,0]
	v_pk_fma_f32 v[92:93], v[148:149], v[8:9], v[92:93] op_sel:[0,1,0]
	v_pk_fma_f32 v[90:91], v[146:147], v[8:9], v[90:91] op_sel:[0,1,0]
	v_pk_fma_f32 v[88:89], v[148:149], v[12:13], v[88:89] op_sel:[0,1,0]
	v_pk_fma_f32 v[86:87], v[146:147], v[12:13], v[86:87] op_sel:[0,1,0]
	v_pk_fma_f32 v[76:77], v[148:149], v[16:17], v[76:77] op_sel:[0,1,0]
	v_pk_fma_f32 v[74:75], v[146:147], v[16:17], v[74:75] op_sel:[0,1,0]
	v_pk_fma_f32 v[72:73], v[148:149], v[20:21], v[72:73] op_sel:[0,1,0]
	v_pk_fma_f32 v[70:71], v[146:147], v[20:21], v[70:71] op_sel:[0,1,0]
	v_pk_fma_f32 v[68:69], v[148:149], v[24:25], v[68:69] op_sel:[0,1,0]
	v_pk_fma_f32 v[66:67], v[146:147], v[24:25], v[66:67] op_sel:[0,1,0]
	v_pk_fma_f32 v[64:65], v[148:149], v[28:29], v[64:65] op_sel:[0,1,0]
	v_pk_fma_f32 v[62:63], v[146:147], v[28:29], v[62:63] op_sel:[0,1,0]
	v_pk_fma_f32 v[60:61], v[148:149], v[32:33], v[60:61] op_sel:[0,1,0]
	v_pk_fma_f32 v[58:59], v[146:147], v[32:33], v[58:59] op_sel:[0,1,0]
	v_pk_fma_f32 v[56:57], v[148:149], v[36:37], v[56:57] op_sel:[0,1,0]
	v_pk_fma_f32 v[54:55], v[146:147], v[36:37], v[54:55] op_sel:[0,1,0]
	v_pk_fma_f32 v[52:53], v[148:149], v[40:41], v[52:53] op_sel:[0,1,0]
	v_pk_fma_f32 v[50:51], v[146:147], v[40:41], v[50:51] op_sel:[0,1,0]
	v_pk_fma_f32 v[48:49], v[148:149], v[80:81], v[48:49] op_sel:[0,1,0]
	v_pk_fma_f32 v[46:47], v[146:147], v[80:81], v[46:47] op_sel:[0,1,0]
	v_pk_fma_f32 v[44:45], v[148:149], v[84:85], v[44:45] op_sel:[0,1,0]
	v_pk_fma_f32 v[42:43], v[146:147], v[84:85], v[42:43] op_sel:[0,1,0]
	ds_read_b128 v[2:5], v124 offset:96
	ds_read_b128 v[6:9], v124 offset:1120
	ds_read_b128 v[10:13], v124 offset:2144
	ds_read_b128 v[14:17], v124 offset:3168
	ds_read_b128 v[18:21], v124 offset:4192
	ds_read_b128 v[22:25], v124 offset:5216
	ds_read_b128 v[26:29], v124 offset:6240
	ds_read_b128 v[30:33], v124 offset:7264
	ds_read_b128 v[34:37], v124 offset:8288
	ds_read_b128 v[38:41], v124 offset:9312
	ds_read_b128 v[78:81], v124 offset:10336
	ds_read_b128 v[82:85], v124 offset:11360
	s_waitcnt vmcnt(7) lgkmcnt(0)
	v_pk_fma_f32 v[96:97], v[152:153], v[2:3], v[96:97] op_sel_hi:[1,0,1]
	v_pk_fma_f32 v[94:95], v[150:151], v[2:3], v[94:95] op_sel_hi:[1,0,1]
	v_pk_fma_f32 v[92:93], v[152:153], v[6:7], v[92:93] op_sel_hi:[1,0,1]
	v_pk_fma_f32 v[90:91], v[150:151], v[6:7], v[90:91] op_sel_hi:[1,0,1]
	v_pk_fma_f32 v[88:89], v[152:153], v[10:11], v[88:89] op_sel_hi:[1,0,1]
	v_pk_fma_f32 v[86:87], v[150:151], v[10:11], v[86:87] op_sel_hi:[1,0,1]
	v_pk_fma_f32 v[76:77], v[152:153], v[14:15], v[76:77] op_sel_hi:[1,0,1]
	v_pk_fma_f32 v[74:75], v[150:151], v[14:15], v[74:75] op_sel_hi:[1,0,1]
	v_pk_fma_f32 v[72:73], v[152:153], v[18:19], v[72:73] op_sel_hi:[1,0,1]
	v_pk_fma_f32 v[70:71], v[150:151], v[18:19], v[70:71] op_sel_hi:[1,0,1]
	v_pk_fma_f32 v[68:69], v[152:153], v[22:23], v[68:69] op_sel_hi:[1,0,1]
	v_pk_fma_f32 v[66:67], v[150:151], v[22:23], v[66:67] op_sel_hi:[1,0,1]
	v_pk_fma_f32 v[64:65], v[152:153], v[26:27], v[64:65] op_sel_hi:[1,0,1]
	v_pk_fma_f32 v[62:63], v[150:151], v[26:27], v[62:63] op_sel_hi:[1,0,1]
	v_pk_fma_f32 v[60:61], v[152:153], v[30:31], v[60:61] op_sel_hi:[1,0,1]
	v_pk_fma_f32 v[58:59], v[150:151], v[30:31], v[58:59] op_sel_hi:[1,0,1]
	v_pk_fma_f32 v[56:57], v[152:153], v[34:35], v[56:57] op_sel_hi:[1,0,1]
	v_pk_fma_f32 v[54:55], v[150:151], v[34:35], v[54:55] op_sel_hi:[1,0,1]
	v_pk_fma_f32 v[52:53], v[152:153], v[38:39], v[52:53] op_sel_hi:[1,0,1]
	v_pk_fma_f32 v[50:51], v[150:151], v[38:39], v[50:51] op_sel_hi:[1,0,1]
	v_pk_fma_f32 v[48:49], v[152:153], v[78:79], v[48:49] op_sel_hi:[1,0,1]
	v_pk_fma_f32 v[46:47], v[150:151], v[78:79], v[46:47] op_sel_hi:[1,0,1]
	v_pk_fma_f32 v[44:45], v[152:153], v[82:83], v[44:45] op_sel_hi:[1,0,1]
	v_pk_fma_f32 v[42:43], v[150:151], v[82:83], v[42:43] op_sel_hi:[1,0,1]
	s_waitcnt vmcnt(6)
	v_pk_fma_f32 v[96:97], v[170:171], v[2:3], v[96:97] op_sel:[0,1,0]
	v_pk_fma_f32 v[94:95], v[168:169], v[2:3], v[94:95] op_sel:[0,1,0]
	v_pk_fma_f32 v[92:93], v[170:171], v[6:7], v[92:93] op_sel:[0,1,0]
	v_pk_fma_f32 v[90:91], v[168:169], v[6:7], v[90:91] op_sel:[0,1,0]
	v_pk_fma_f32 v[88:89], v[170:171], v[10:11], v[88:89] op_sel:[0,1,0]
	v_pk_fma_f32 v[86:87], v[168:169], v[10:11], v[86:87] op_sel:[0,1,0]
	v_pk_fma_f32 v[76:77], v[170:171], v[14:15], v[76:77] op_sel:[0,1,0]
	v_pk_fma_f32 v[74:75], v[168:169], v[14:15], v[74:75] op_sel:[0,1,0]
	v_pk_fma_f32 v[72:73], v[170:171], v[18:19], v[72:73] op_sel:[0,1,0]
	v_pk_fma_f32 v[70:71], v[168:169], v[18:19], v[70:71] op_sel:[0,1,0]
	v_pk_fma_f32 v[68:69], v[170:171], v[22:23], v[68:69] op_sel:[0,1,0]
	v_pk_fma_f32 v[66:67], v[168:169], v[22:23], v[66:67] op_sel:[0,1,0]
	v_pk_fma_f32 v[64:65], v[170:171], v[26:27], v[64:65] op_sel:[0,1,0]
	v_pk_fma_f32 v[62:63], v[168:169], v[26:27], v[62:63] op_sel:[0,1,0]
	v_pk_fma_f32 v[60:61], v[170:171], v[30:31], v[60:61] op_sel:[0,1,0]
	v_pk_fma_f32 v[58:59], v[168:169], v[30:31], v[58:59] op_sel:[0,1,0]
	v_pk_fma_f32 v[56:57], v[170:171], v[34:35], v[56:57] op_sel:[0,1,0]
	v_pk_fma_f32 v[54:55], v[168:169], v[34:35], v[54:55] op_sel:[0,1,0]
	v_pk_fma_f32 v[52:53], v[170:171], v[38:39], v[52:53] op_sel:[0,1,0]
	v_pk_fma_f32 v[50:51], v[168:169], v[38:39], v[50:51] op_sel:[0,1,0]
	v_pk_fma_f32 v[48:49], v[170:171], v[78:79], v[48:49] op_sel:[0,1,0]
	v_pk_fma_f32 v[46:47], v[168:169], v[78:79], v[46:47] op_sel:[0,1,0]
	v_pk_fma_f32 v[44:45], v[170:171], v[82:83], v[44:45] op_sel:[0,1,0]
	v_pk_fma_f32 v[42:43], v[168:169], v[82:83], v[42:43] op_sel:[0,1,0]
	s_waitcnt vmcnt(5)
	v_pk_fma_f32 v[96:97], v[174:175], v[4:5], v[96:97] op_sel_hi:[1,0,1]
	v_pk_fma_f32 v[94:95], v[172:173], v[4:5], v[94:95] op_sel_hi:[1,0,1]
	v_pk_fma_f32 v[92:93], v[174:175], v[8:9], v[92:93] op_sel_hi:[1,0,1]
	v_pk_fma_f32 v[90:91], v[172:173], v[8:9], v[90:91] op_sel_hi:[1,0,1]
	v_pk_fma_f32 v[88:89], v[174:175], v[12:13], v[88:89] op_sel_hi:[1,0,1]
	v_pk_fma_f32 v[86:87], v[172:173], v[12:13], v[86:87] op_sel_hi:[1,0,1]
	v_pk_fma_f32 v[76:77], v[174:175], v[16:17], v[76:77] op_sel_hi:[1,0,1]
	v_pk_fma_f32 v[74:75], v[172:173], v[16:17], v[74:75] op_sel_hi:[1,0,1]
	v_pk_fma_f32 v[72:73], v[174:175], v[20:21], v[72:73] op_sel_hi:[1,0,1]
	v_pk_fma_f32 v[70:71], v[172:173], v[20:21], v[70:71] op_sel_hi:[1,0,1]
	v_pk_fma_f32 v[68:69], v[174:175], v[24:25], v[68:69] op_sel_hi:[1,0,1]
	v_pk_fma_f32 v[66:67], v[172:173], v[24:25], v[66:67] op_sel_hi:[1,0,1]
	v_pk_fma_f32 v[64:65], v[174:175], v[28:29], v[64:65] op_sel_hi:[1,0,1]
	v_pk_fma_f32 v[62:63], v[172:173], v[28:29], v[62:63] op_sel_hi:[1,0,1]
	v_pk_fma_f32 v[60:61], v[174:175], v[32:33], v[60:61] op_sel_hi:[1,0,1]
	v_pk_fma_f32 v[58:59], v[172:173], v[32:33], v[58:59] op_sel_hi:[1,0,1]
	v_pk_fma_f32 v[56:57], v[174:175], v[36:37], v[56:57] op_sel_hi:[1,0,1]
	v_pk_fma_f32 v[54:55], v[172:173], v[36:37], v[54:55] op_sel_hi:[1,0,1]
	v_pk_fma_f32 v[52:53], v[174:175], v[40:41], v[52:53] op_sel_hi:[1,0,1]
	v_pk_fma_f32 v[50:51], v[172:173], v[40:41], v[50:51] op_sel_hi:[1,0,1]
	v_pk_fma_f32 v[48:49], v[174:175], v[80:81], v[48:49] op_sel_hi:[1,0,1]
	v_pk_fma_f32 v[46:47], v[172:173], v[80:81], v[46:47] op_sel_hi:[1,0,1]
	v_pk_fma_f32 v[44:45], v[174:175], v[84:85], v[44:45] op_sel_hi:[1,0,1]
	v_pk_fma_f32 v[42:43], v[172:173], v[84:85], v[42:43] op_sel_hi:[1,0,1]
	s_waitcnt vmcnt(4)
	v_pk_fma_f32 v[96:97], v[178:179], v[4:5], v[96:97] op_sel:[0,1,0]
	v_pk_fma_f32 v[94:95], v[176:177], v[4:5], v[94:95] op_sel:[0,1,0]
	v_pk_fma_f32 v[92:93], v[178:179], v[8:9], v[92:93] op_sel:[0,1,0]
	v_pk_fma_f32 v[90:91], v[176:177], v[8:9], v[90:91] op_sel:[0,1,0]
	v_pk_fma_f32 v[88:89], v[178:179], v[12:13], v[88:89] op_sel:[0,1,0]
	v_pk_fma_f32 v[86:87], v[176:177], v[12:13], v[86:87] op_sel:[0,1,0]
	v_pk_fma_f32 v[76:77], v[178:179], v[16:17], v[76:77] op_sel:[0,1,0]
	v_pk_fma_f32 v[74:75], v[176:177], v[16:17], v[74:75] op_sel:[0,1,0]
	v_pk_fma_f32 v[72:73], v[178:179], v[20:21], v[72:73] op_sel:[0,1,0]
	v_pk_fma_f32 v[70:71], v[176:177], v[20:21], v[70:71] op_sel:[0,1,0]
	v_pk_fma_f32 v[68:69], v[178:179], v[24:25], v[68:69] op_sel:[0,1,0]
	v_pk_fma_f32 v[66:67], v[176:177], v[24:25], v[66:67] op_sel:[0,1,0]
	v_pk_fma_f32 v[64:65], v[178:179], v[28:29], v[64:65] op_sel:[0,1,0]
	v_pk_fma_f32 v[62:63], v[176:177], v[28:29], v[62:63] op_sel:[0,1,0]
	v_pk_fma_f32 v[60:61], v[178:179], v[32:33], v[60:61] op_sel:[0,1,0]
	v_pk_fma_f32 v[58:59], v[176:177], v[32:33], v[58:59] op_sel:[0,1,0]
	v_pk_fma_f32 v[56:57], v[178:179], v[36:37], v[56:57] op_sel:[0,1,0]
	v_pk_fma_f32 v[54:55], v[176:177], v[36:37], v[54:55] op_sel:[0,1,0]
	v_pk_fma_f32 v[52:53], v[178:179], v[40:41], v[52:53] op_sel:[0,1,0]
	v_pk_fma_f32 v[50:51], v[176:177], v[40:41], v[50:51] op_sel:[0,1,0]
	v_pk_fma_f32 v[48:49], v[178:179], v[80:81], v[48:49] op_sel:[0,1,0]
	v_pk_fma_f32 v[46:47], v[176:177], v[80:81], v[46:47] op_sel:[0,1,0]
	v_pk_fma_f32 v[44:45], v[178:179], v[84:85], v[44:45] op_sel:[0,1,0]
	v_pk_fma_f32 v[42:43], v[176:177], v[84:85], v[42:43] op_sel:[0,1,0]
	ds_read_b128 v[2:5], v124 offset:112
	ds_read_b128 v[6:9], v124 offset:1136
	ds_read_b128 v[10:13], v124 offset:2160
	ds_read_b128 v[14:17], v124 offset:3184
	ds_read_b128 v[18:21], v124 offset:4208
	ds_read_b128 v[22:25], v124 offset:5232
	ds_read_b128 v[26:29], v124 offset:6256
	ds_read_b128 v[30:33], v124 offset:7280
	ds_read_b128 v[34:37], v124 offset:8304
	ds_read_b128 v[38:41], v124 offset:9328
	ds_read_b128 v[78:81], v124 offset:10352
	ds_read_b128 v[82:85], v124 offset:11376
	s_waitcnt vmcnt(3) lgkmcnt(0)
	v_pk_fma_f32 v[96:97], v[182:183], v[2:3], v[96:97] op_sel_hi:[1,0,1]
	v_pk_fma_f32 v[94:95], v[180:181], v[2:3], v[94:95] op_sel_hi:[1,0,1]
	v_pk_fma_f32 v[92:93], v[182:183], v[6:7], v[92:93] op_sel_hi:[1,0,1]
	v_pk_fma_f32 v[90:91], v[180:181], v[6:7], v[90:91] op_sel_hi:[1,0,1]
	v_pk_fma_f32 v[88:89], v[182:183], v[10:11], v[88:89] op_sel_hi:[1,0,1]
	v_pk_fma_f32 v[86:87], v[180:181], v[10:11], v[86:87] op_sel_hi:[1,0,1]
	v_pk_fma_f32 v[76:77], v[182:183], v[14:15], v[76:77] op_sel_hi:[1,0,1]
	v_pk_fma_f32 v[74:75], v[180:181], v[14:15], v[74:75] op_sel_hi:[1,0,1]
	v_pk_fma_f32 v[72:73], v[182:183], v[18:19], v[72:73] op_sel_hi:[1,0,1]
	v_pk_fma_f32 v[70:71], v[180:181], v[18:19], v[70:71] op_sel_hi:[1,0,1]
	v_pk_fma_f32 v[68:69], v[182:183], v[22:23], v[68:69] op_sel_hi:[1,0,1]
	v_pk_fma_f32 v[66:67], v[180:181], v[22:23], v[66:67] op_sel_hi:[1,0,1]
	v_pk_fma_f32 v[64:65], v[182:183], v[26:27], v[64:65] op_sel_hi:[1,0,1]
	v_pk_fma_f32 v[62:63], v[180:181], v[26:27], v[62:63] op_sel_hi:[1,0,1]
	v_pk_fma_f32 v[60:61], v[182:183], v[30:31], v[60:61] op_sel_hi:[1,0,1]
	v_pk_fma_f32 v[58:59], v[180:181], v[30:31], v[58:59] op_sel_hi:[1,0,1]
	v_pk_fma_f32 v[56:57], v[182:183], v[34:35], v[56:57] op_sel_hi:[1,0,1]
	v_pk_fma_f32 v[54:55], v[180:181], v[34:35], v[54:55] op_sel_hi:[1,0,1]
	v_pk_fma_f32 v[52:53], v[182:183], v[38:39], v[52:53] op_sel_hi:[1,0,1]
	v_pk_fma_f32 v[50:51], v[180:181], v[38:39], v[50:51] op_sel_hi:[1,0,1]
	v_pk_fma_f32 v[48:49], v[182:183], v[78:79], v[48:49] op_sel_hi:[1,0,1]
	v_pk_fma_f32 v[46:47], v[180:181], v[78:79], v[46:47] op_sel_hi:[1,0,1]
	v_pk_fma_f32 v[44:45], v[182:183], v[82:83], v[44:45] op_sel_hi:[1,0,1]
	v_pk_fma_f32 v[42:43], v[180:181], v[82:83], v[42:43] op_sel_hi:[1,0,1]
	s_waitcnt vmcnt(2)
	v_pk_fma_f32 v[96:97], v[186:187], v[2:3], v[96:97] op_sel:[0,1,0]
	v_pk_fma_f32 v[94:95], v[184:185], v[2:3], v[94:95] op_sel:[0,1,0]
	v_pk_fma_f32 v[92:93], v[186:187], v[6:7], v[92:93] op_sel:[0,1,0]
	v_pk_fma_f32 v[90:91], v[184:185], v[6:7], v[90:91] op_sel:[0,1,0]
	v_pk_fma_f32 v[88:89], v[186:187], v[10:11], v[88:89] op_sel:[0,1,0]
	v_pk_fma_f32 v[86:87], v[184:185], v[10:11], v[86:87] op_sel:[0,1,0]
	v_pk_fma_f32 v[76:77], v[186:187], v[14:15], v[76:77] op_sel:[0,1,0]
	v_pk_fma_f32 v[74:75], v[184:185], v[14:15], v[74:75] op_sel:[0,1,0]
	v_pk_fma_f32 v[72:73], v[186:187], v[18:19], v[72:73] op_sel:[0,1,0]
	v_pk_fma_f32 v[70:71], v[184:185], v[18:19], v[70:71] op_sel:[0,1,0]
	v_pk_fma_f32 v[68:69], v[186:187], v[22:23], v[68:69] op_sel:[0,1,0]
	v_pk_fma_f32 v[66:67], v[184:185], v[22:23], v[66:67] op_sel:[0,1,0]
	v_pk_fma_f32 v[64:65], v[186:187], v[26:27], v[64:65] op_sel:[0,1,0]
	v_pk_fma_f32 v[62:63], v[184:185], v[26:27], v[62:63] op_sel:[0,1,0]
	v_pk_fma_f32 v[60:61], v[186:187], v[30:31], v[60:61] op_sel:[0,1,0]
	v_pk_fma_f32 v[58:59], v[184:185], v[30:31], v[58:59] op_sel:[0,1,0]
	v_pk_fma_f32 v[56:57], v[186:187], v[34:35], v[56:57] op_sel:[0,1,0]
	v_pk_fma_f32 v[54:55], v[184:185], v[34:35], v[54:55] op_sel:[0,1,0]
	v_pk_fma_f32 v[52:53], v[186:187], v[38:39], v[52:53] op_sel:[0,1,0]
	v_pk_fma_f32 v[50:51], v[184:185], v[38:39], v[50:51] op_sel:[0,1,0]
	v_pk_fma_f32 v[48:49], v[186:187], v[78:79], v[48:49] op_sel:[0,1,0]
	v_pk_fma_f32 v[46:47], v[184:185], v[78:79], v[46:47] op_sel:[0,1,0]
	v_pk_fma_f32 v[44:45], v[186:187], v[82:83], v[44:45] op_sel:[0,1,0]
	v_pk_fma_f32 v[42:43], v[184:185], v[82:83], v[42:43] op_sel:[0,1,0]
	s_waitcnt vmcnt(1)
	v_pk_fma_f32 v[96:97], v[190:191], v[4:5], v[96:97] op_sel_hi:[1,0,1]
	v_pk_fma_f32 v[94:95], v[188:189], v[4:5], v[94:95] op_sel_hi:[1,0,1]
	v_pk_fma_f32 v[92:93], v[190:191], v[8:9], v[92:93] op_sel_hi:[1,0,1]
	v_pk_fma_f32 v[90:91], v[188:189], v[8:9], v[90:91] op_sel_hi:[1,0,1]
	v_pk_fma_f32 v[88:89], v[190:191], v[12:13], v[88:89] op_sel_hi:[1,0,1]
	v_pk_fma_f32 v[86:87], v[188:189], v[12:13], v[86:87] op_sel_hi:[1,0,1]
	v_pk_fma_f32 v[76:77], v[190:191], v[16:17], v[76:77] op_sel_hi:[1,0,1]
	v_pk_fma_f32 v[74:75], v[188:189], v[16:17], v[74:75] op_sel_hi:[1,0,1]
	v_pk_fma_f32 v[72:73], v[190:191], v[20:21], v[72:73] op_sel_hi:[1,0,1]
	v_pk_fma_f32 v[70:71], v[188:189], v[20:21], v[70:71] op_sel_hi:[1,0,1]
	v_pk_fma_f32 v[68:69], v[190:191], v[24:25], v[68:69] op_sel_hi:[1,0,1]
	v_pk_fma_f32 v[66:67], v[188:189], v[24:25], v[66:67] op_sel_hi:[1,0,1]
	v_pk_fma_f32 v[64:65], v[190:191], v[28:29], v[64:65] op_sel_hi:[1,0,1]
	v_pk_fma_f32 v[62:63], v[188:189], v[28:29], v[62:63] op_sel_hi:[1,0,1]
	v_pk_fma_f32 v[60:61], v[190:191], v[32:33], v[60:61] op_sel_hi:[1,0,1]
	v_pk_fma_f32 v[58:59], v[188:189], v[32:33], v[58:59] op_sel_hi:[1,0,1]
	v_pk_fma_f32 v[56:57], v[190:191], v[36:37], v[56:57] op_sel_hi:[1,0,1]
	v_pk_fma_f32 v[54:55], v[188:189], v[36:37], v[54:55] op_sel_hi:[1,0,1]
	v_pk_fma_f32 v[52:53], v[190:191], v[40:41], v[52:53] op_sel_hi:[1,0,1]
	v_pk_fma_f32 v[50:51], v[188:189], v[40:41], v[50:51] op_sel_hi:[1,0,1]
	v_pk_fma_f32 v[48:49], v[190:191], v[80:81], v[48:49] op_sel_hi:[1,0,1]
	v_pk_fma_f32 v[46:47], v[188:189], v[80:81], v[46:47] op_sel_hi:[1,0,1]
	v_pk_fma_f32 v[44:45], v[190:191], v[84:85], v[44:45] op_sel_hi:[1,0,1]
	v_pk_fma_f32 v[42:43], v[188:189], v[84:85], v[42:43] op_sel_hi:[1,0,1]
	s_waitcnt vmcnt(0)
	v_pk_fma_f32 v[96:97], v[194:195], v[4:5], v[96:97] op_sel:[0,1,0]
	v_pk_fma_f32 v[94:95], v[192:193], v[4:5], v[94:95] op_sel:[0,1,0]
	v_pk_fma_f32 v[92:93], v[194:195], v[8:9], v[92:93] op_sel:[0,1,0]
	v_pk_fma_f32 v[90:91], v[192:193], v[8:9], v[90:91] op_sel:[0,1,0]
	v_pk_fma_f32 v[88:89], v[194:195], v[12:13], v[88:89] op_sel:[0,1,0]
	v_pk_fma_f32 v[86:87], v[192:193], v[12:13], v[86:87] op_sel:[0,1,0]
	v_pk_fma_f32 v[76:77], v[194:195], v[16:17], v[76:77] op_sel:[0,1,0]
	v_pk_fma_f32 v[74:75], v[192:193], v[16:17], v[74:75] op_sel:[0,1,0]
	v_pk_fma_f32 v[72:73], v[194:195], v[20:21], v[72:73] op_sel:[0,1,0]
	v_pk_fma_f32 v[70:71], v[192:193], v[20:21], v[70:71] op_sel:[0,1,0]
	v_pk_fma_f32 v[68:69], v[194:195], v[24:25], v[68:69] op_sel:[0,1,0]
	v_pk_fma_f32 v[66:67], v[192:193], v[24:25], v[66:67] op_sel:[0,1,0]
	v_pk_fma_f32 v[64:65], v[194:195], v[28:29], v[64:65] op_sel:[0,1,0]
	v_pk_fma_f32 v[62:63], v[192:193], v[28:29], v[62:63] op_sel:[0,1,0]
	v_pk_fma_f32 v[60:61], v[194:195], v[32:33], v[60:61] op_sel:[0,1,0]
	v_pk_fma_f32 v[58:59], v[192:193], v[32:33], v[58:59] op_sel:[0,1,0]
	v_pk_fma_f32 v[56:57], v[194:195], v[36:37], v[56:57] op_sel:[0,1,0]
	v_pk_fma_f32 v[54:55], v[192:193], v[36:37], v[54:55] op_sel:[0,1,0]
	v_pk_fma_f32 v[52:53], v[194:195], v[40:41], v[52:53] op_sel:[0,1,0]
	v_pk_fma_f32 v[50:51], v[192:193], v[40:41], v[50:51] op_sel:[0,1,0]
	v_pk_fma_f32 v[48:49], v[194:195], v[80:81], v[48:49] op_sel:[0,1,0]
	v_pk_fma_f32 v[46:47], v[192:193], v[80:81], v[46:47] op_sel:[0,1,0]
	v_pk_fma_f32 v[44:45], v[194:195], v[84:85], v[44:45] op_sel:[0,1,0]
	v_pk_fma_f32 v[42:43], v[192:193], v[84:85], v[42:43] op_sel:[0,1,0]
	ds_write_b128 v123, v[94:97] offset:12288
	ds_write_b128 v123, v[90:93] offset:13312
	ds_write_b128 v123, v[86:89] offset:14336
	ds_write_b128 v123, v[74:77] offset:15360
	ds_write_b128 v123, v[70:73] offset:16384
	ds_write_b128 v123, v[66:69] offset:17408
	ds_write_b128 v123, v[62:65] offset:18432
	ds_write_b128 v123, v[58:61] offset:19456
	ds_write_b128 v123, v[54:57] offset:20480
	ds_write_b128 v123, v[50:53] offset:21504
	ds_write_b128 v123, v[46:49] offset:22528
	ds_write_b128 v123, v[42:45] offset:23552
	s_waitcnt lgkmcnt(0)
	s_barrier
	s_and_saveexec_b64 s[44:45], s[0:1]
	s_cbranch_execz .LBB0_831
	s_mul_i32 s48, s12, 12
	v_lshl_add_u64 v[2:3], s[42:43], 2, v[106:107]
	s_mov_b64 s[12:13], -1
	v_mov_b32_e32 v0, v166
	s_and_saveexec_b64 s[42:43], s[38:39]
	s_cbranch_execz .LBB0_842
	s_mov_b32 s12, s48
	s_mov_b64 s[46:47], 0
	v_mov_b32_e32 v0, v120
	v_mov_b64_e32 v[4:5], v[166:167]
	s_mov_b32 s13, 0xc000

.LBB0_918:
	s_or_b64 exec, exec, s[12:13]
	v_cvt_f32_u32_e32 v5, v3
	s_waitcnt vmcnt(0)
	v_readfirstlane_b32 s12, v4
	v_sub_u32_e32 v4, 0, v3
	v_rcp_iflag_f32_e32 v5, v5
	v_add_u32_e32 v6, s12, v0
	v_mul_f32_e32 v5, 0x4f7ffffe, v5
	v_cvt_u32_f32_e32 v5, v5
	v_mul_lo_u32 v0, v4, v5
	v_mul_hi_u32 v0, v5, v0
	v_add_u32_e32 v0, v5, v0
	v_mul_hi_u32 v0, v6, v0
	v_mul_lo_u32 v4, v0, v3
	v_sub_u32_e32 v4, v6, v4
	v_add_u32_e32 v5, 1, v0
	v_cmp_ge_u32_e32 vcc, v4, v3
	s_nop 1
	v_cndmask_b32_e32 v0, v0, v5, vcc
	v_sub_u32_e32 v5, v4, v3
	v_cndmask_b32_e32 v4, v4, v5, vcc
	v_add_u32_e32 v5, 1, v0
	v_cmp_ge_u32_e32 vcc, v4, v3
	v_add_u32_e32 v4, 1, v6
	s_nop 0
	v_cndmask_b32_e32 v0, v0, v5, vcc
	v_mul_lo_u32 v5, v3, v0
	v_add_u32_e32 v3, v5, v3
	v_cmp_ne_u32_e32 vcc, v4, v3
	s_waitcnt lgkmcnt(0)
	v_add_u32_e32 v5, 1, v0
	v_mul_lo_u32 v5, v5, v2
	v_readlane_b32 s12, v252, 47
	v_readlane_b32 s13, v252, 48
	s_nop 4
	s_cbranch_vccnz .Lbr_poll
	buffer_wbl2 sc1
	s_waitcnt vmcnt(0)
	global_atomic_add v1, v203, s[12:13]
.Lbr_poll:
	global_load_dword v6, v1, s[12:13] sc1
	s_waitcnt vmcnt(0)
	v_cmp_lt_u32_e32 vcc, v6, v5
	s_cbranch_vccz .Lbr_done
	s_sleep 1
	s_branch .Lbr_poll
.Lbr_done:
	buffer_inv sc1
	s_branch .Ltr_7
